# wait-fix all 9 gemm loops + XCD-aware tile remap (outproj x2, glu) + prep stores write-through with no per-WG L2 flush at the first grid sync
# speedup vs baseline: 1.0531x; 1.0139x over previous
.LBB0_5:
	s_mov_b32 s9, s8
	s_or_b64 s[4:5], s[8:9], s[2:3]
	v_cmp_le_u32_e32 vcc, s5, v1
	v_cmp_le_u32_e64 s[4:5], s4, v2
	s_and_saveexec_b64 s[10:11], s[4:5]
	s_cbranch_execz .LBB0_7
	v_readlane_b32 s4, v237, 3
	v_mov_b32_e32 v4, v6
	v_readlane_b32 s5, v237, 4
	s_nop 1
	v_lshl_add_u64 v[8:9], v[4:5], 2, s[4:5]
	global_store_dword v[8:9], v5, off sc0 sc1
.LBB0_7:
	s_or_b64 exec, exec, s[10:11]
	s_and_saveexec_b64 s[4:5], vcc
	s_cbranch_execz .LBB0_4
	v_readlane_b32 s10, v237, 3
	v_mov_b32_e32 v4, v7
	v_readlane_b32 s11, v237, 4
	s_nop 1
	v_lshl_add_u64 v[8:9], v[4:5], 2, s[10:11]
	global_store_dword v[8:9], v5, off sc0 sc1
	s_branch .LBB0_4

.LBB0_10:
	s_load_dwordx16 s[36:51], s[0:1], 0x0
	s_lshl_b32 s78, s24, 8
	v_mov_b32_e32 v1, v128
	s_movk_i32 s2, 0x200
	v_add_u32_e32 v2, s78, v1
	v_cmp_gt_i32_e32 vcc, s2, v2
	v_ashrrev_i32_e32 v3, 31, v2
	s_and_saveexec_b64 s[2:3], vcc
	s_cbranch_execz .LBB0_12
	v_lshlrev_b64 v[4:5], 2, v[2:3]
	v_lshl_add_u64 v[6:7], s[88:89], 0, v[4:5]
	v_add_co_u32_e32 v8, vcc, 0x3d00000, v6
	s_waitcnt lgkmcnt(0)
	v_lshl_add_u64 v[4:5], s[38:39], 0, v[4:5]
	s_mov_b64 s[4:5], vcc
	v_add_co_u32_e32 v10, vcc, 0x1000, v4
	s_mov_b32 s6, 0x3fb8aa3b
	s_nop 0
	v_addc_co_u32_e32 v11, vcc, 0, v5, vcc
	global_load_dword v1, v[4:5], off
	global_load_dword v9, v[4:5], off offset:2048
	global_load_dword v12, v[10:11], off
	s_mov_b32 s7, 0xc2ce8ed0
	s_mov_b32 s8, 0x42b17218
	v_mov_b32_e32 v5, 0x7f800000
	v_mov_b32_e32 v4, 0
	s_waitcnt vmcnt(0)
	v_max3_f32 v10, v1, v9, v12
	v_sub_f32_e32 v1, v1, v10
	v_sub_f32_e32 v11, v9, v10
	v_mul_f32_e32 v9, 0x3fb8aa3b, v1
	v_sub_f32_e32 v10, v12, v10
	v_mul_f32_e32 v12, 0x3fb8aa3b, v11
	v_fma_f32 v14, v1, s6, -v9
	v_rndne_f32_e32 v15, v9
	v_mul_f32_e32 v13, 0x3fb8aa3b, v10
	v_fma_f32 v16, v11, s6, -v12
	v_rndne_f32_e32 v17, v12
	v_fmac_f32_e32 v14, 0x32a5705f, v1
	v_sub_f32_e32 v9, v9, v15
	v_fma_f32 v18, v10, s6, -v13
	v_rndne_f32_e32 v19, v13
	v_fmac_f32_e32 v16, 0x32a5705f, v11
	v_sub_f32_e32 v12, v12, v17
	v_add_f32_e32 v9, v9, v14
	v_cvt_i32_f32_e32 v15, v15
	v_fmac_f32_e32 v18, 0x32a5705f, v10
	v_sub_f32_e32 v13, v13, v19
	v_add_f32_e32 v12, v12, v16
	v_exp_f32_e32 v14, v9
	v_cvt_i32_f32_e32 v17, v17
	v_add_f32_e32 v13, v13, v18
	v_exp_f32_e32 v12, v12
	v_cvt_i32_f32_e32 v19, v19
	v_exp_f32_e32 v13, v13
	v_addc_co_u32_e64 v9, vcc, 0, v7, s[4:5]
	v_ldexp_f32 v14, v14, v15
	v_cmp_ngt_f32_e32 vcc, s7, v1
	v_ldexp_f32 v12, v12, v17
	v_ldexp_f32 v13, v13, v19
	v_cndmask_b32_e32 v14, 0, v14, vcc
	v_cmp_ngt_f32_e32 vcc, s7, v11
	global_store_dword v[8:9], v4, off sc0 sc1
	s_nop 0
	v_cndmask_b32_e32 v12, 0, v12, vcc
	v_cmp_ngt_f32_e32 vcc, s7, v10
	s_nop 1
	v_cndmask_b32_e32 v13, 0, v13, vcc
	v_cmp_nlt_f32_e32 vcc, s8, v1
	s_nop 1
	v_cndmask_b32_e32 v1, v5, v14, vcc
	v_cmp_nlt_f32_e32 vcc, s8, v11
	s_nop 1
	v_cndmask_b32_e32 v11, v5, v12, vcc
	v_cmp_nlt_f32_e32 vcc, s8, v10
	v_add_f32_e32 v10, v1, v11
	s_nop 0
	v_cndmask_b32_e32 v5, v5, v13, vcc
	v_add_f32_e32 v5, v5, v10
	v_div_scale_f32 v10, s[4:5], v5, v5, v1
	v_rcp_f32_e32 v11, v10
	v_div_scale_f32 v4, vcc, v1, v5, v1
	v_fma_f32 v8, -v10, v11, 1.0
	v_fmac_f32_e32 v11, v8, v11
	v_mul_f32_e32 v8, v4, v11
	v_fma_f32 v9, -v10, v8, v4
	v_fmac_f32_e32 v8, v9, v11
	v_fma_f32 v4, -v10, v8, v4
	v_div_fmas_f32 v8, v4, v11, v8
	v_add_co_u32_e32 v4, vcc, 0x3d01000, v6
	v_div_fixup_f32 v1, v8, v5, v1
	s_nop 0
	v_addc_co_u32_e32 v5, vcc, 0, v7, vcc
	global_store_dword v[4:5], v1, off sc0 sc1

.LBB0_21:
	s_or_b64 exec, exec, s[4:5]
	s_waitcnt vmcnt(0)
	v_mul_f32_e32 v7, v7, v4
	s_mov_b32 s4, 0x3fb8aa3b
	v_mul_f32_e32 v10, 0x3fb8aa3b, v7
	v_fma_f32 v13, v7, s4, -v10
	v_rndne_f32_e32 v14, v10
	v_fmamk_f32 v13, v7, 0x32a5705f, v13
	v_sub_f32_e32 v10, v10, v14
	v_add_f32_e32 v10, v10, v13
	v_exp_f32_e32 v10, v10
	v_cvt_i32_f32_e32 v13, v14
	s_mov_b32 s4, 0xc2ce8ed0
	v_cmp_ngt_f32_e32 vcc, s4, v7
	s_mov_b32 s4, 0x42b17218
	v_ldexp_f32 v10, v10, v13
	v_cndmask_b32_e32 v10, 0, v10, vcc
	v_mov_b32_e32 v13, 0x7f800000
	v_cmp_nlt_f32_e32 vcc, s4, v7
	v_mul_f32_e32 v7, v9, v9
	s_brev_b32 s4, 1
	v_cndmask_b32_e32 v13, v13, v10, vcc
	v_mov_b32_e32 v10, 0x3c0881c4
	v_fmamk_f32 v14, v7, 0xb94c1982, v10
	v_fmaak_f32 v14, v7, v14, 0xbe2aaa9d
	v_mul_f32_e32 v14, v7, v14
	v_fmac_f32_e32 v9, v9, v14
	v_mov_b32_e32 v14, 0xbab64f3b
	v_fmamk_f32 v16, v7, 0x37d75334, v14
	v_fmaak_f32 v16, v7, v16, 0x3d2aabf7
	v_fmaak_f32 v16, v7, v16, 0xbf000004
	v_fma_f32 v7, v7, v16, 1.0
	v_and_b32_e32 v16, 1, v8
	v_cmp_eq_u32_e32 vcc, 0, v16
	v_lshlrev_b32_e32 v8, 30, v8
	v_mov_b32_e32 v15, 0xbe2aaa9d
	v_cndmask_b32_e64 v7, -v9, v7, vcc
	v_bitop3_b32 v7, v8, v7, s4 bitop3:0x6c
	s_movk_i32 s4, 0x1f8
	v_mov_b32_e32 v9, 0x7fc00000
	v_cmp_class_f32_e64 vcc, v5, s4
	v_mov_b32_e32 v17, 0x3d2aabf7
	v_mov_b32_e32 v18, 0xbf000004
	v_cndmask_b32_e32 v16, v9, v7, vcc
	v_mul_f32_e32 v7, v12, v12
	v_fmac_f32_e32 v10, 0xb94c1982, v7
	v_fmac_f32_e32 v15, v7, v10
	v_mul_f32_e32 v10, v7, v15
	v_fmac_f32_e32 v14, 0x37d75334, v7
	v_fmac_f32_e32 v12, v12, v10
	v_fmac_f32_e32 v17, v7, v14
	v_and_b32_e32 v10, 1, v11
	v_fmac_f32_e32 v18, v7, v17
	v_cmp_eq_u32_e64 s[4:5], 0, v10
	v_lshlrev_b32_e32 v10, 30, v11
	v_fma_f32 v7, v7, v18, 1.0
	v_and_b32_e32 v10, 0x80000000, v10
	v_xor_b32_e32 v5, v6, v5
	v_cndmask_b32_e64 v7, v7, v12, s[4:5]
	v_xor_b32_e32 v5, v5, v10
	v_lshlrev_b32_e32 v6, 1, v2
	v_xor_b32_e32 v5, v5, v7
	v_ashrrev_i32_e32 v7, 31, v6
	v_cndmask_b32_e32 v5, v9, v5, vcc
	v_lshl_add_u64 v[6:7], v[6:7], 2, s[88:89]
	s_mov_b32 s4, 0x3d02000
	v_mul_f32_e32 v9, v13, v5
	v_add_co_u32_e32 v10, vcc, s4, v6
	v_mul_f32_e32 v8, v13, v16
	s_nop 0
	v_addc_co_u32_e32 v11, vcc, 0, v7, vcc
	v_mul_f32_e32 v5, v9, v9
	global_store_dwordx2 v[10:11], v[8:9], off sc0 sc1
	v_fma_f32 v5, v8, v8, -v5
	v_add_f32_e32 v8, v8, v8
	v_mul_f32_e32 v8, v8, v9
	v_mul_f32_e32 v10, v8, v8
	v_fma_f32 v10, v5, v5, -v10
	v_add_f32_e32 v5, v5, v5
	v_mul_f32_e32 v5, v8, v5
	v_mul_f32_e32 v8, v5, v5
	v_fma_f32 v8, v10, v10, -v8
	v_add_f32_e32 v10, v10, v10
	v_mul_f32_e32 v5, v5, v10
	v_mul_f32_e32 v10, v5, v5
	v_fma_f32 v10, v8, v8, -v10
	v_add_f32_e32 v8, v8, v8
	v_mul_f32_e32 v5, v5, v8
	v_mul_f32_e32 v8, v5, v5
	v_fma_f32 v8, v10, v10, -v8
	v_add_f32_e32 v10, v10, v10
	v_mul_f32_e32 v5, v5, v10
	v_mul_f32_e32 v10, v5, v5
	s_mov_b32 s4, 0x3d06000
	v_fma_f32 v10, v8, v8, -v10
	v_add_f32_e32 v8, v8, v8
	v_add_co_u32_e32 v6, vcc, s4, v6
	v_mul_f32_e32 v11, v5, v8
	s_nop 0
	v_addc_co_u32_e32 v7, vcc, 0, v7, vcc
	global_store_dwordx2 v[6:7], v[10:11], off sc0 sc1
	v_lshlrev_b32_e32 v6, 4, v2
	v_ashrrev_i32_e32 v7, 31, v6
	v_lshlrev_b64 v[6:7], 2, v[6:7]
	v_lshl_add_u64 v[10:11], s[50:51], 0, v[6:7]
	s_load_dwordx16 s[44:59], s[0:1], 0x40
	v_mul_f32_e32 v5, v1, v1
	v_fma_f32 v13, v13, v16, -1.0
	v_mul_f32_e32 v14, v1, v9
	v_fmac_f32_e32 v14, v4, v13
	s_waitcnt lgkmcnt(0)
	v_lshl_add_u64 v[6:7], s[44:45], 0, v[6:7]
	global_load_dword v8, v[6:7], off
	global_load_dword v12, v[10:11], off
	v_fmac_f32_e32 v5, v4, v4
	v_div_scale_f32 v15, s[4:5], v5, v5, v14
	v_rcp_f32_e32 v16, v15
	v_mul_f32_e32 v1, v1, v13
	v_fma_f32 v1, v4, v9, -v1
	v_lshlrev_b64 v[2:3], 7, v[2:3]
	v_fma_f32 v4, -v15, v16, 1.0
	v_fmac_f32_e32 v16, v4, v16
	v_div_scale_f32 v4, vcc, v14, v5, v14
	v_mul_f32_e32 v9, v4, v16
	v_fma_f32 v13, -v15, v9, v4
	v_fmac_f32_e32 v9, v13, v16
	v_div_scale_f32 v13, s[4:5], v5, v5, v1
	v_fma_f32 v4, -v15, v9, v4
	v_rcp_f32_e32 v15, v13
	v_div_fmas_f32 v4, v4, v16, v9
	v_div_fixup_f32 v9, v4, v5, v14
	v_lshl_add_u64 v[2:3], s[88:89], 0, v[2:3]
	v_fma_f32 v4, -v13, v15, 1.0
	v_fmac_f32_e32 v15, v4, v15
	v_div_scale_f32 v4, vcc, v1, v5, v1
	v_mul_f32_e32 v14, v4, v15
	v_fma_f32 v16, -v13, v14, v4
	v_fmac_f32_e32 v14, v16, v15
	v_fma_f32 v4, -v13, v14, v4
	v_div_fmas_f32 v4, v4, v15, v14
	s_mov_b64 s[4:5], 0x3d0a000
	v_div_fixup_f32 v1, v4, v5, v1
	v_lshl_add_u64 v[4:5], v[2:3], 0, s[4:5]
	s_mov_b32 s4, 0x3d0a000
	v_add_co_u32_e32 v2, vcc, s4, v2
	s_waitcnt vmcnt(1)
	v_mul_f32_e32 v13, v8, v1
	s_waitcnt vmcnt(0)
	v_fma_f32 v13, v12, v9, -v13
	v_addc_co_u32_e32 v3, vcc, 0, v3, vcc
	global_store_dword v[2:3], v13, off sc0 sc1
	v_mul_f32_e32 v2, v8, v9
	v_fmac_f32_e32 v2, v12, v1
	global_store_dword v[4:5], v2, off offset:64 sc0 sc1
	global_load_dword v2, v[6:7], off offset:4
	s_nop 0
	global_load_dword v3, v[10:11], off offset:4
	s_waitcnt vmcnt(1)
	v_mul_f32_e32 v8, v2, v1
	v_mul_f32_e32 v2, v2, v9
	s_waitcnt vmcnt(0)
	v_fma_f32 v8, v3, v9, -v8
	v_fmac_f32_e32 v2, v3, v1
	global_store_dword v[4:5], v8, off offset:4 sc0 sc1
	global_store_dword v[4:5], v2, off offset:68 sc0 sc1
	global_load_dword v2, v[6:7], off offset:8
	s_nop 0
	global_load_dword v3, v[10:11], off offset:8
	s_waitcnt vmcnt(1)
	v_mul_f32_e32 v8, v1, v2
	v_mul_f32_e32 v2, v9, v2
	s_waitcnt vmcnt(0)
	v_fma_f32 v8, v9, v3, -v8
	v_fmac_f32_e32 v2, v1, v3
	global_store_dword v[4:5], v8, off offset:8 sc0 sc1
	global_store_dword v[4:5], v2, off offset:72 sc0 sc1
	global_load_dword v2, v[6:7], off offset:12
	s_nop 0
	global_load_dword v3, v[10:11], off offset:12
	s_waitcnt vmcnt(1)
	v_mul_f32_e32 v8, v1, v2
	v_mul_f32_e32 v2, v9, v2
	s_waitcnt vmcnt(0)
	v_fma_f32 v8, v9, v3, -v8
	v_fmac_f32_e32 v2, v1, v3
	global_store_dword v[4:5], v8, off offset:12 sc0 sc1
	global_store_dword v[4:5], v2, off offset:76 sc0 sc1
	global_load_dword v2, v[6:7], off offset:16
	s_nop 0
	global_load_dword v3, v[10:11], off offset:16
	s_waitcnt vmcnt(1)
	v_mul_f32_e32 v8, v1, v2
	v_mul_f32_e32 v2, v9, v2
	s_waitcnt vmcnt(0)
	v_fma_f32 v8, v9, v3, -v8
	v_fmac_f32_e32 v2, v1, v3
	global_store_dword v[4:5], v8, off offset:16 sc0 sc1
	global_store_dword v[4:5], v2, off offset:80 sc0 sc1
	global_load_dword v2, v[6:7], off offset:20
	s_nop 0
	global_load_dword v3, v[10:11], off offset:20
	s_waitcnt vmcnt(1)
	v_mul_f32_e32 v8, v1, v2
	v_mul_f32_e32 v2, v9, v2
	s_waitcnt vmcnt(0)
	v_fma_f32 v8, v9, v3, -v8
	v_fmac_f32_e32 v2, v1, v3
	global_store_dword v[4:5], v8, off offset:20 sc0 sc1
	global_store_dword v[4:5], v2, off offset:84 sc0 sc1
	global_load_dword v2, v[6:7], off offset:24
	s_nop 0
	global_load_dword v3, v[10:11], off offset:24
	s_waitcnt vmcnt(1)
	v_mul_f32_e32 v8, v1, v2
	v_mul_f32_e32 v2, v9, v2
	s_waitcnt vmcnt(0)
	v_fma_f32 v8, v9, v3, -v8
	v_fmac_f32_e32 v2, v1, v3
	global_store_dword v[4:5], v8, off offset:24 sc0 sc1
	global_store_dword v[4:5], v2, off offset:88 sc0 sc1
	global_load_dword v2, v[6:7], off offset:28
	s_nop 0
	global_load_dword v3, v[10:11], off offset:28
	s_waitcnt vmcnt(1)
	v_mul_f32_e32 v8, v1, v2
	v_mul_f32_e32 v2, v9, v2
	s_waitcnt vmcnt(0)
	v_fma_f32 v8, v9, v3, -v8
	v_fmac_f32_e32 v2, v1, v3
	global_store_dword v[4:5], v8, off offset:28 sc0 sc1
	global_store_dword v[4:5], v2, off offset:92 sc0 sc1
	global_load_dword v2, v[6:7], off offset:32
	s_nop 0
	global_load_dword v3, v[10:11], off offset:32
	s_waitcnt vmcnt(1)
	v_mul_f32_e32 v8, v1, v2
	v_mul_f32_e32 v2, v9, v2
	s_waitcnt vmcnt(0)
	v_fma_f32 v8, v9, v3, -v8
	v_fmac_f32_e32 v2, v1, v3
	global_store_dword v[4:5], v8, off offset:32 sc0 sc1
	global_store_dword v[4:5], v2, off offset:96 sc0 sc1
	global_load_dword v2, v[6:7], off offset:36
	s_nop 0
	global_load_dword v3, v[10:11], off offset:36
	s_waitcnt vmcnt(1)
	v_mul_f32_e32 v8, v1, v2
	v_mul_f32_e32 v2, v9, v2
	s_waitcnt vmcnt(0)
	v_fma_f32 v8, v9, v3, -v8
	v_fmac_f32_e32 v2, v1, v3
	global_store_dword v[4:5], v8, off offset:36 sc0 sc1
	global_store_dword v[4:5], v2, off offset:100 sc0 sc1
	global_load_dword v2, v[6:7], off offset:40
	s_nop 0
	global_load_dword v3, v[10:11], off offset:40
	s_waitcnt vmcnt(1)
	v_mul_f32_e32 v8, v1, v2
	v_mul_f32_e32 v2, v9, v2
	s_waitcnt vmcnt(0)
	v_fma_f32 v8, v9, v3, -v8
	v_fmac_f32_e32 v2, v1, v3
	global_store_dword v[4:5], v8, off offset:40 sc0 sc1
	global_store_dword v[4:5], v2, off offset:104 sc0 sc1
	global_load_dword v2, v[6:7], off offset:44
	s_nop 0
	global_load_dword v3, v[10:11], off offset:44
	s_waitcnt vmcnt(1)
	v_mul_f32_e32 v8, v1, v2
	v_mul_f32_e32 v2, v9, v2
	s_waitcnt vmcnt(0)
	v_fma_f32 v8, v9, v3, -v8
	v_fmac_f32_e32 v2, v1, v3
	global_store_dword v[4:5], v8, off offset:44 sc0 sc1
	global_store_dword v[4:5], v2, off offset:108 sc0 sc1
	global_load_dword v2, v[6:7], off offset:48
	s_nop 0
	global_load_dword v3, v[10:11], off offset:48
	s_waitcnt vmcnt(1)
	v_mul_f32_e32 v8, v1, v2
	v_mul_f32_e32 v2, v9, v2
	s_waitcnt vmcnt(0)
	v_fma_f32 v8, v9, v3, -v8
	v_fmac_f32_e32 v2, v1, v3
	global_store_dword v[4:5], v8, off offset:48 sc0 sc1
	global_store_dword v[4:5], v2, off offset:112 sc0 sc1
	global_load_dword v2, v[6:7], off offset:52
	s_nop 0
	global_load_dword v3, v[10:11], off offset:52
	s_waitcnt vmcnt(1)
	v_mul_f32_e32 v8, v1, v2
	v_mul_f32_e32 v2, v9, v2
	s_waitcnt vmcnt(0)
	v_fma_f32 v8, v9, v3, -v8
	v_fmac_f32_e32 v2, v1, v3
	global_store_dword v[4:5], v8, off offset:52 sc0 sc1
	global_store_dword v[4:5], v2, off offset:116 sc0 sc1
	global_load_dword v2, v[6:7], off offset:56
	s_nop 0
	global_load_dword v3, v[10:11], off offset:56
	s_waitcnt vmcnt(1)
	v_mul_f32_e32 v8, v1, v2
	v_mul_f32_e32 v2, v9, v2
	s_waitcnt vmcnt(0)
	v_fma_f32 v8, v9, v3, -v8
	v_fmac_f32_e32 v2, v1, v3
	global_store_dword v[4:5], v8, off offset:56 sc0 sc1
	global_store_dword v[4:5], v2, off offset:120 sc0 sc1
	global_load_dword v2, v[6:7], off offset:60
	s_nop 0
	global_load_dword v3, v[10:11], off offset:60
	s_waitcnt vmcnt(1)
	v_mul_f32_e32 v6, v1, v2
	v_mul_f32_e32 v2, v9, v2
	s_waitcnt vmcnt(0)
	v_fma_f32 v6, v9, v3, -v6
	v_fmac_f32_e32 v2, v1, v3
	global_store_dword v[4:5], v6, off offset:60 sc0 sc1
	global_store_dword v[4:5], v2, off offset:124 sc0 sc1

.LBB0_24:
	s_mul_hi_i32 s1, s0, 0x66666667
	s_lshr_b32 s2, s1, 31
	s_ashr_i32 s1, s1, 8
	s_add_i32 s1, s1, s2
	s_mul_i32 s2, s1, 0xfffffd80
	s_add_i32 s2, s0, s2
	s_mul_hi_i32 s2, s2, 0x66666667
	s_lshr_b32 s3, s2, 31
	s_ashr_i32 s2, s2, 4
	s_add_i32 s4, s0, s90
	s_add_i32 s5, s2, s3
	s_cmpk_lt_u32 s4, 0x280
	s_cselect_b32 s2, s4, s0
	s_mul_hi_i32 s3, s2, 0x66666667
	s_lshr_b32 s6, s3, 31
	s_ashr_i32 s3, s3, 8
	s_add_i32 s3, s3, s6
	s_mul_i32 s6, s3, 0xfffffd80
	s_add_i32 s6, s6, s2
	s_mul_hi_i32 s2, s6, 0x66666667
	s_lshr_b32 s8, s2, 31
	s_ashr_i32 s2, s2, 4
	s_add_i32 s2, s2, s8
	s_mul_i32 s8, s2, 0xffffffd8
	s_mul_hi_i32 s7, s3, 0xa00000
	s_mul_i32 s3, s3, 0xa00000
	s_add_i32 s8, s8, s6
	s_add_u32 s3, s40, s3
	s_mul_i32 s9, s2, 0xa0000
	s_addc_u32 s6, s41, s7
	s_lshl_b32 s2, s2, 6
	s_mul_hi_i32 s2, s2, 0x2800
	s_add_u32 s7, s3, s9
	s_addc_u32 s6, s6, s2
	s_lshl_b32 s2, s8, 6
	s_ashr_i32 s3, s2, 31
	s_lshl_b64 s[2:3], s[2:3], 2
	s_add_u32 s2, s7, s2
	s_addc_u32 s3, s6, s3
	v_lshl_add_u64 v[36:37], s[2:3], 0, v[18:19]
	v_lshl_add_u64 v[38:39], v[20:21], 2, v[36:37]
	v_lshl_add_u64 v[40:41], v[22:23], 2, v[36:37]
	v_lshl_add_u64 v[44:45], v[24:25], 2, v[36:37]
	v_lshl_add_u64 v[48:49], v[26:27], 2, v[36:37]
	global_load_dwordx4 v[36:39], v[38:39], off
	s_nop 0
	global_load_dwordx4 v[40:43], v[40:41], off
	s_nop 0
	global_load_dwordx4 v[44:47], v[44:45], off
	s_nop 0
	global_load_dwordx4 v[48:51], v[48:49], off
	s_mul_i32 s2, s1, 0x280
	s_mul_i32 s6, s5, 0xffffffd8
	s_sub_i32 s2, s6, s2
	s_mul_hi_i32 s3, s1, 0x500000
	s_mul_i32 s1, s1, 0x500000
	s_add_i32 s2, s0, s2
	s_add_u32 s1, s88, s1
	s_addc_u32 s6, s89, s3
	s_lshl_b32 s7, s2, 6
	s_lshl_b32 s2, s5, 6
	s_waitcnt vmcnt(4)
	v_cvt_pk_bf16_f32 v14, v14, s0
	v_cvt_pk_bf16_f32 v6, v6, s0
	v_cvt_pk_bf16_f32 v7, v7, s0
	v_cvt_pk_bf16_f32 v8, v8, s0
	v_cvt_pk_bf16_f32 v9, v9, s0
	v_cvt_pk_bf16_f32 v2, v2, s0
	v_cvt_pk_bf16_f32 v3, v3, s0
	v_cvt_pk_bf16_f32 v4, v4, s0
	v_cvt_pk_bf16_f32 v5, v5, s0
	s_ashr_i32 s3, s2, 31
	v_cvt_pk_bf16_f32 v15, v15, s0
	v_cvt_pk_bf16_f32 v16, v16, s0
	v_cvt_pk_bf16_f32 v17, v17, s0
	v_cvt_pk_bf16_f32 v10, v10, s0
	v_cvt_pk_bf16_f32 v11, v11, s0
	v_cvt_pk_bf16_f32 v12, v12, s0
	v_cvt_pk_bf16_f32 v13, v13, s0
	s_waitcnt lgkmcnt(0)
	s_barrier
	ds_write_b16 v1, v14
	ds_write_b16 v1, v15 offset:144
	ds_write_b16 v1, v16 offset:288
	ds_write_b16 v1, v17 offset:432
	ds_write_b16 v1, v10 offset:32
	ds_write_b16 v1, v11 offset:176
	ds_write_b16 v1, v12 offset:320
	ds_write_b16 v1, v13 offset:464
	ds_write_b16 v1, v6 offset:64
	ds_write_b16 v1, v7 offset:208
	ds_write_b16 v1, v8 offset:352
	ds_write_b16 v1, v9 offset:496
	ds_write_b16 v1, v2 offset:96
	ds_write_b16 v1, v3 offset:240
	ds_write_b16 v1, v4 offset:384
	ds_write_b16 v1, v5 offset:528
	s_waitcnt lgkmcnt(0)
	s_barrier
	ds_read_b128 v[2:5], v28
	ds_read_b128 v[6:9], v30
	s_lshl_b64 s[2:3], s[2:3], 1
	v_add_u32_e32 v10, s7, v34
	v_add_u32_e32 v12, s7, v29
	s_add_u32 s2, s1, s2
	v_ashrrev_i32_e32 v11, 31, v10
	v_ashrrev_i32_e32 v13, 31, v12
	s_addc_u32 s3, s6, s3
	v_lshlrev_b64 v[10:11], 11, v[10:11]
	v_lshlrev_b64 v[12:13], 11, v[12:13]
	v_lshl_add_u64 v[14:15], s[2:3], 0, v[32:33]
	v_lshl_add_u64 v[10:11], v[14:15], 0, v[10:11]
	v_lshl_add_u64 v[12:13], v[14:15], 0, v[12:13]
	s_mov_b32 s0, s4
	s_cmpk_lt_i32 s4, 0x280
	s_waitcnt lgkmcnt(1)
	global_store_dwordx4 v[10:11], v[2:5], off sc0 sc1
	s_waitcnt lgkmcnt(0)
	global_store_dwordx4 v[12:13], v[6:9], off sc0 sc1
	s_waitcnt vmcnt(5)
	v_mov_b64_e32 v[14:15], v[36:37]
	v_mov_b64_e32 v[16:17], v[38:39]
	s_waitcnt vmcnt(4)
	v_mov_b64_e32 v[10:11], v[40:41]
	v_mov_b64_e32 v[12:13], v[42:43]
	s_waitcnt vmcnt(3)
	v_mov_b64_e32 v[6:7], v[44:45]
	v_mov_b64_e32 v[8:9], v[46:47]
	s_waitcnt vmcnt(2)
	v_mov_b64_e32 v[2:3], v[48:49]
	v_mov_b64_e32 v[4:5], v[50:51]
	s_cbranch_scc1 .LBB0_24

.LBB0_27:
	s_ashr_i32 s0, s6, 31
	s_waitcnt vmcnt(0)
	v_cvt_pk_bf16_f32 v37, v14, s0
	v_cvt_pk_bf16_f32 v42, v15, s0
	v_cvt_pk_bf16_f32 v43, v16, s0
	v_cvt_pk_bf16_f32 v44, v17, s0
	v_cvt_pk_bf16_f32 v45, v10, s0
	v_cvt_pk_bf16_f32 v46, v11, s0
	v_cvt_pk_bf16_f32 v47, v12, s0
	v_cvt_pk_bf16_f32 v48, v13, s0
	v_cvt_pk_bf16_f32 v49, v6, s0
	v_cvt_pk_bf16_f32 v50, v7, s0
	v_cvt_pk_bf16_f32 v51, v8, s0
	v_cvt_pk_bf16_f32 v52, v9, s0
	s_lshr_b32 s0, s0, 25
	s_add_i32 s1, s6, s0
	s_ashr_i32 s0, s1, 7
	s_and_b32 s1, s1, 0xffffff80
	s_sub_i32 s1, s6, s1
	s_ashr_i32 s7, s1, 31
	s_lshr_b32 s7, s7, 28
	s_add_i32 s1, s1, s7
	s_add_i32 s5, s6, s90
	s_ashr_i32 s14, s1, 4
	s_cmpk_lt_u32 s5, 0x80
	s_cselect_b32 s1, s5, s6
	s_ashr_i32 s6, s1, 31
	s_lshr_b32 s6, s6, 25
	s_add_i32 s7, s1, s6
	s_ashr_i32 s6, s7, 7
	s_and_b32 s7, s7, 0xffffff80
	s_sub_i32 s1, s1, s7
	s_ashr_i32 s8, s1, 31
	s_lshr_b32 s8, s8, 28
	s_ashr_i32 s7, s6, 31
	s_add_i32 s8, s1, s8
	s_lshl_b64 s[6:7], s[6:7], 21
	s_ashr_i32 s8, s8, 4
	s_add_u32 s9, s52, s6
	s_addc_u32 s15, s53, s7
	s_lshl_b32 s6, s8, 6
	s_ashr_i32 s7, s6, 31
	s_lshl_b64 s[6:7], s[6:7], 12
	s_add_u32 s9, s9, s6
	s_addc_u32 s15, s15, s7
	s_lshl_b32 s6, s8, 10
	s_lshl_b32 s1, s1, 6
	s_sub_i32 s6, s1, s6
	s_ashr_i32 s7, s6, 31
	s_lshl_b64 s[6:7], s[6:7], 2
	s_add_u32 s6, s9, s6
	s_addc_u32 s7, s15, s7
	v_lshl_add_u64 v[6:7], s[6:7], 0, v[18:19]
	v_lshl_add_u64 v[8:9], v[20:21], 2, v[6:7]
	v_lshl_add_u64 v[10:11], v[22:23], 2, v[6:7]
	v_lshl_add_u64 v[38:39], v[24:25], 2, v[6:7]
	v_lshl_add_u64 v[40:41], v[26:27], 2, v[6:7]
	global_load_dwordx4 v[14:17], v[8:9], off
	s_nop 0
	global_load_dwordx4 v[10:13], v[10:11], off
	s_nop 0
	global_load_dwordx4 v[6:9], v[38:39], off
	s_nop 0
	global_load_dwordx4 v[38:41], v[40:41], off
	s_ashr_i32 s1, s0, 31
	s_lshl_b64 s[8:9], s[0:1], 20
	s_add_u32 s1, s10, s8
	s_addc_u32 s7, s11, s9
	s_lshl_b32 s8, s14, 6
	s_ashr_i32 s9, s8, 31
	s_lshl_b32 s15, s14, 10
	s_lshl_b64 s[8:9], s[8:9], 1
	s_add_u32 s8, s1, s8
	s_addc_u32 s9, s7, s9
	s_lshl_b32 s7, s0, 13
	v_cvt_pk_bf16_f32 v2, v2, s0
	v_cvt_pk_bf16_f32 v3, v3, s0
	v_cvt_pk_bf16_f32 v4, v4, s0
	v_cvt_pk_bf16_f32 v5, v5, s0
	v_add_u32_e32 v53, s2, v34
	s_add_i32 s0, s15, s7
	v_add_u32_e32 v54, s2, v29
	s_waitcnt lgkmcnt(0)
	s_barrier
	ds_write_b16 v1, v37
	ds_write_b16 v1, v42 offset:144
	ds_write_b16 v1, v43 offset:288
	ds_write_b16 v1, v44 offset:432
	ds_write_b16 v1, v45 offset:32
	ds_write_b16 v1, v46 offset:176
	ds_write_b16 v1, v47 offset:320
	ds_write_b16 v1, v48 offset:464
	ds_write_b16 v1, v49 offset:64
	ds_write_b16 v1, v50 offset:208
	ds_write_b16 v1, v51 offset:352
	ds_write_b16 v1, v52 offset:496
	ds_write_b16 v1, v2 offset:96
	ds_write_b16 v1, v3 offset:240
	ds_write_b16 v1, v4 offset:384
	ds_write_b16 v1, v5 offset:528
	v_subrev_u32_e32 v37, s0, v53
	v_subrev_u32_e32 v48, s0, v54
	v_cmp_gt_i32_e32 vcc, s4, v37
	v_cmp_gt_i32_e64 s[0:1], s4, v48
	s_waitcnt lgkmcnt(0)
	v_cndmask_b32_e64 v37, v36, 0, vcc
	v_cndmask_b32_e64 v48, v36, 0, s[0:1]
	v_subrev_u32_e32 v37, s15, v37
	v_subrev_u32_e32 v48, s15, v48
	v_subrev_u32_e32 v37, s7, v37
	v_subrev_u32_e32 v48, s7, v48
	v_add_lshl_u32 v37, v53, v37, 1
	s_barrier
	ds_read_b128 v[2:5], v28
	ds_read_b128 v[42:45], v30
	v_cndmask_b32_e64 v49, 32, 0, vcc
	v_add_lshl_u32 v48, v54, v48, 1
	v_and_b32_e32 v37, 0xffffffc0, v37
	v_cndmask_b32_e64 v50, 32, 0, s[0:1]
	v_and_b32_e32 v51, 0xffffffc0, v48
	v_or3_b32 v48, v49, v31, v37
	v_or3_b32 v50, v50, v35, v51
	v_ashrrev_i32_e32 v49, 31, v48
	v_lshl_add_u64 v[46:47], s[8:9], 0, v[32:33]
	v_ashrrev_i32_e32 v51, 31, v50
	v_lshlrev_b64 v[48:49], 10, v[48:49]
	s_add_i32 s2, s2, s3
	v_lshlrev_b64 v[50:51], 10, v[50:51]
	v_lshl_add_u64 v[48:49], v[46:47], 0, v[48:49]
	s_mov_b32 s6, s5
	s_cmpk_lt_i32 s5, 0x80
	v_lshl_add_u64 v[46:47], v[46:47], 0, v[50:51]
	s_waitcnt lgkmcnt(1)
	global_store_dwordx4 v[48:49], v[2:5], off sc0 sc1
	s_waitcnt lgkmcnt(0)
	global_store_dwordx4 v[46:47], v[42:45], off sc0 sc1
	s_waitcnt vmcnt(2)
	v_mov_b64_e32 v[2:3], v[38:39]
	v_mov_b64_e32 v[4:5], v[40:41]
	s_cbranch_scc1 .LBB0_27

.LBB0_30:
	s_ashr_i32 s2, s6, 31
	s_lshr_b32 s2, s2, 24
	s_add_i32 s3, s6, s2
	s_ashr_i32 s2, s3, 8
	s_and_b32 s3, s3, 0xffffff00
	s_sub_i32 s3, s6, s3
	s_ashr_i32 s7, s3, 31
	s_lshr_b32 s7, s7, 28
	s_add_i32 s3, s3, s7
	s_add_i32 s16, s6, s90
	s_ashr_i32 s17, s3, 4
	s_cmpk_lt_u32 s16, 0x100
	s_cselect_b32 s3, s16, s6
	s_ashr_i32 s6, s3, 31
	s_lshr_b32 s6, s6, 24
	s_add_i32 s7, s3, s6
	s_ashr_i32 s6, s7, 8
	s_and_b32 s7, s7, 0xffffff00
	s_sub_i32 s3, s3, s7
	s_ashr_i32 s14, s3, 31
	s_lshr_b32 s14, s14, 28
	s_ashr_i32 s7, s6, 31
	s_add_i32 s14, s3, s14
	s_lshl_b64 s[6:7], s[6:7], 22
	s_ashr_i32 s14, s14, 4
	s_add_u32 s15, s26, s6
	s_addc_u32 s18, s27, s7
	s_lshl_b32 s6, s14, 6
	s_ashr_i32 s7, s6, 31
	s_lshl_b64 s[6:7], s[6:7], 12
	s_add_u32 s15, s15, s6
	s_addc_u32 s18, s18, s7
	s_lshl_b32 s6, s14, 10
	s_lshl_b32 s3, s3, 6
	s_sub_i32 s6, s3, s6
	s_ashr_i32 s7, s6, 31
	s_lshl_b64 s[6:7], s[6:7], 2
	s_add_u32 s6, s15, s6
	s_addc_u32 s7, s18, s7
	v_lshl_add_u64 v[36:37], s[6:7], 0, v[18:19]
	v_lshl_add_u64 v[38:39], v[20:21], 2, v[36:37]
	v_lshl_add_u64 v[40:41], v[22:23], 2, v[36:37]
	v_lshl_add_u64 v[44:45], v[24:25], 2, v[36:37]
	v_lshl_add_u64 v[48:49], v[26:27], 2, v[36:37]
	global_load_dwordx4 v[36:39], v[38:39], off
	s_nop 0
	global_load_dwordx4 v[40:43], v[40:41], off
	s_nop 0
	global_load_dwordx4 v[44:47], v[44:45], off
	s_nop 0
	global_load_dwordx4 v[48:51], v[48:49], off
	s_ashr_i32 s3, s2, 31
	s_lshl_b64 s[14:15], s[2:3], 21
	s_add_u32 s3, s8, s14
	s_addc_u32 s7, s9, s15
	s_lshl_b32 s14, s17, 6
	s_ashr_i32 s15, s14, 31
	s_lshl_b64 s[14:15], s[14:15], 1
	s_add_u32 s14, s3, s14
	s_addc_u32 s15, s7, s15
	s_lshl_b32 s3, s17, 10
	s_lshl_b32 s2, s2, 14
	s_waitcnt vmcnt(4)
	v_cvt_pk_bf16_f32 v14, v14, s0
	v_cvt_pk_bf16_f32 v6, v6, s0
	v_cvt_pk_bf16_f32 v7, v7, s0
	v_cvt_pk_bf16_f32 v8, v8, s0
	v_cvt_pk_bf16_f32 v9, v9, s0
	v_cvt_pk_bf16_f32 v2, v2, s0
	v_cvt_pk_bf16_f32 v3, v3, s0
	v_cvt_pk_bf16_f32 v4, v4, s0
	v_cvt_pk_bf16_f32 v5, v5, s0
	s_add_i32 s3, s3, s2
	v_cvt_pk_bf16_f32 v15, v15, s0
	v_cvt_pk_bf16_f32 v16, v16, s0
	v_cvt_pk_bf16_f32 v17, v17, s0
	v_cvt_pk_bf16_f32 v10, v10, s0
	v_cvt_pk_bf16_f32 v11, v11, s0
	v_cvt_pk_bf16_f32 v12, v12, s0
	v_cvt_pk_bf16_f32 v13, v13, s0
	s_waitcnt lgkmcnt(0)
	s_barrier
	ds_write_b16 v1, v14
	ds_write_b16 v1, v15 offset:144
	ds_write_b16 v1, v16 offset:288
	ds_write_b16 v1, v17 offset:432
	ds_write_b16 v1, v10 offset:32
	ds_write_b16 v1, v11 offset:176
	ds_write_b16 v1, v12 offset:320
	ds_write_b16 v1, v13 offset:464
	ds_write_b16 v1, v6 offset:64
	ds_write_b16 v1, v7 offset:208
	ds_write_b16 v1, v8 offset:352
	ds_write_b16 v1, v9 offset:496
	ds_write_b16 v1, v2 offset:96
	ds_write_b16 v1, v3 offset:240
	ds_write_b16 v1, v4 offset:384
	ds_write_b16 v1, v5 offset:528
	s_waitcnt lgkmcnt(0)
	s_barrier
	ds_read_b128 v[2:5], v28
	ds_read_b128 v[6:9], v30
	s_sub_i32 s2, s4, s3
	v_add_u32_e32 v12, s2, v34
	v_add_u32_e32 v14, s2, v29
	v_ashrrev_i32_e32 v13, 31, v12
	v_ashrrev_i32_e32 v15, 31, v14
	v_lshl_add_u64 v[10:11], s[14:15], 0, v[32:33]
	v_lshlrev_b64 v[12:13], 11, v[12:13]
	v_lshlrev_b64 v[14:15], 11, v[14:15]
	s_add_i32 s4, s4, s5
	v_lshl_add_u64 v[12:13], v[10:11], 0, v[12:13]
	v_lshl_add_u64 v[10:11], v[10:11], 0, v[14:15]
	s_mov_b32 s6, s16
	s_cmpk_lt_i32 s16, 0x100
	s_waitcnt lgkmcnt(1)
	global_store_dwordx4 v[12:13], v[2:5], off sc0 sc1
	s_waitcnt lgkmcnt(0)
	global_store_dwordx4 v[10:11], v[6:9], off sc0 sc1
	s_waitcnt vmcnt(5)
	v_mov_b64_e32 v[14:15], v[36:37]
	v_mov_b64_e32 v[16:17], v[38:39]
	s_waitcnt vmcnt(4)
	v_mov_b64_e32 v[10:11], v[40:41]
	v_mov_b64_e32 v[12:13], v[42:43]
	s_waitcnt vmcnt(3)
	v_mov_b64_e32 v[6:7], v[44:45]
	v_mov_b64_e32 v[8:9], v[46:47]
	s_waitcnt vmcnt(2)
	v_mov_b64_e32 v[2:3], v[48:49]
	v_mov_b64_e32 v[4:5], v[50:51]
	s_cbranch_scc1 .LBB0_30

.LBB0_33:
	s_mul_hi_i32 s3, s2, 0x2aaaaaab
	s_lshr_b32 s4, s3, 31
	s_ashr_i32 s3, s3, 6
	s_add_i32 s3, s3, s4
	s_mul_i32 s4, s3, 0xfffffe80
	s_add_i32 s4, s2, s4
	s_mul_hi_i32 s4, s4, 0x2aaaaaab
	s_lshr_b32 s5, s4, 31
	s_ashr_i32 s4, s4, 2
	s_add_i32 s6, s2, s90
	s_add_i32 s7, s4, s5
	s_cmpk_lt_u32 s6, 0x180
	s_cselect_b32 s4, s6, s2
	s_mul_hi_i32 s5, s4, 0x2aaaaaab
	s_lshr_b32 s14, s5, 31
	s_ashr_i32 s5, s5, 6
	s_add_i32 s5, s5, s14
	s_mul_i32 s14, s5, 0xfffffe80
	s_add_i32 s14, s14, s4
	s_mul_hi_i32 s4, s14, 0x2aaaaaab
	s_lshr_b32 s16, s4, 31
	s_ashr_i32 s4, s4, 2
	s_add_i32 s4, s4, s16
	s_mul_i32 s16, s4, 0xffffffe8
	s_mul_hi_i32 s15, s5, 0x600000
	s_mul_i32 s5, s5, 0x600000
	s_add_i32 s16, s16, s14
	s_add_u32 s5, s28, s5
	s_mul_i32 s17, s4, 0x60000
	s_addc_u32 s14, s29, s15
	s_lshl_b32 s4, s4, 6
	s_mul_hi_i32 s4, s4, 0x1800
	s_add_u32 s15, s5, s17
	s_addc_u32 s14, s14, s4
	s_lshl_b32 s4, s16, 6
	s_ashr_i32 s5, s4, 31
	s_lshl_b64 s[4:5], s[4:5], 2
	s_add_u32 s4, s15, s4
	s_addc_u32 s5, s14, s5
	v_lshl_add_u64 v[36:37], s[4:5], 0, v[18:19]
	v_lshl_add_u64 v[38:39], v[20:21], 2, v[36:37]
	v_lshl_add_u64 v[40:41], v[22:23], 2, v[36:37]
	v_lshl_add_u64 v[44:45], v[24:25], 2, v[36:37]
	v_lshl_add_u64 v[48:49], v[26:27], 2, v[36:37]
	global_load_dwordx4 v[36:39], v[38:39], off
	s_nop 0
	global_load_dwordx4 v[40:43], v[40:41], off
	s_nop 0
	global_load_dwordx4 v[44:47], v[44:45], off
	s_nop 0
	global_load_dwordx4 v[48:51], v[48:49], off
	s_mul_i32 s4, s3, 0x180
	s_mul_i32 s14, s7, 0xffffffe8
	s_sub_i32 s4, s14, s4
	s_mul_hi_i32 s5, s3, 0x300000
	s_mul_i32 s3, s3, 0x300000
	s_add_i32 s4, s2, s4
	s_add_u32 s3, s18, s3
	s_addc_u32 s14, s19, s5
	s_lshl_b32 s15, s4, 6
	s_lshl_b32 s4, s7, 6
	s_waitcnt vmcnt(4)
	v_cvt_pk_bf16_f32 v14, v14, s0
	v_cvt_pk_bf16_f32 v6, v6, s0
	v_cvt_pk_bf16_f32 v7, v7, s0
	v_cvt_pk_bf16_f32 v8, v8, s0
	v_cvt_pk_bf16_f32 v9, v9, s0
	v_cvt_pk_bf16_f32 v2, v2, s0
	v_cvt_pk_bf16_f32 v3, v3, s0
	v_cvt_pk_bf16_f32 v4, v4, s0
	v_cvt_pk_bf16_f32 v5, v5, s0
	s_ashr_i32 s5, s4, 31
	v_cvt_pk_bf16_f32 v15, v15, s0
	v_cvt_pk_bf16_f32 v16, v16, s0
	v_cvt_pk_bf16_f32 v17, v17, s0
	v_cvt_pk_bf16_f32 v10, v10, s0
	v_cvt_pk_bf16_f32 v11, v11, s0
	v_cvt_pk_bf16_f32 v12, v12, s0
	v_cvt_pk_bf16_f32 v13, v13, s0
	s_waitcnt lgkmcnt(0)
	s_barrier
	ds_write_b16 v1, v14
	ds_write_b16 v1, v15 offset:144
	ds_write_b16 v1, v16 offset:288
	ds_write_b16 v1, v17 offset:432
	ds_write_b16 v1, v10 offset:32
	ds_write_b16 v1, v11 offset:176
	ds_write_b16 v1, v12 offset:320
	ds_write_b16 v1, v13 offset:464
	ds_write_b16 v1, v6 offset:64
	ds_write_b16 v1, v7 offset:208
	ds_write_b16 v1, v8 offset:352
	ds_write_b16 v1, v9 offset:496
	ds_write_b16 v1, v2 offset:96
	ds_write_b16 v1, v3 offset:240
	ds_write_b16 v1, v4 offset:384
	ds_write_b16 v1, v5 offset:528
	s_waitcnt lgkmcnt(0)
	s_barrier
	ds_read_b128 v[2:5], v28
	ds_read_b128 v[6:9], v30
	s_lshl_b64 s[4:5], s[4:5], 1
	v_add_u32_e32 v10, s15, v34
	v_add_u32_e32 v12, s15, v29
	s_add_u32 s4, s3, s4
	v_ashrrev_i32_e32 v11, 31, v10
	v_ashrrev_i32_e32 v13, 31, v12
	s_addc_u32 s5, s14, s5
	v_lshlrev_b64 v[10:11], 11, v[10:11]
	v_lshlrev_b64 v[12:13], 11, v[12:13]
	v_lshl_add_u64 v[14:15], s[4:5], 0, v[32:33]
	v_lshl_add_u64 v[10:11], v[14:15], 0, v[10:11]
	v_lshl_add_u64 v[12:13], v[14:15], 0, v[12:13]
	s_mov_b32 s2, s6
	s_cmpk_lt_i32 s6, 0x180
	s_waitcnt lgkmcnt(1)
	global_store_dwordx4 v[10:11], v[2:5], off sc0 sc1
	s_waitcnt lgkmcnt(0)
	global_store_dwordx4 v[12:13], v[6:9], off sc0 sc1
	s_waitcnt vmcnt(5)
	v_mov_b64_e32 v[14:15], v[36:37]
	v_mov_b64_e32 v[16:17], v[38:39]
	s_waitcnt vmcnt(4)
	v_mov_b64_e32 v[10:11], v[40:41]
	v_mov_b64_e32 v[12:13], v[42:43]
	s_waitcnt vmcnt(3)
	v_mov_b64_e32 v[6:7], v[44:45]
	v_mov_b64_e32 v[8:9], v[46:47]
	s_waitcnt vmcnt(2)
	v_mov_b64_e32 v[2:3], v[48:49]
	v_mov_b64_e32 v[4:5], v[50:51]
	s_cbranch_scc1 .LBB0_33

.LBB0_36:
	s_ashr_i32 s0, s4, 31
	s_lshr_b32 s0, s0, 24
	s_add_i32 s1, s4, s0
	s_ashr_i32 s0, s1, 8
	s_and_b32 s1, s1, 0xffffff00
	s_sub_i32 s1, s4, s1
	s_ashr_i32 s5, s1, 31
	s_lshr_b32 s5, s5, 28
	s_add_i32 s1, s1, s5
	s_add_i32 s14, s4, s90
	s_ashr_i32 s15, s1, 4
	s_cmpk_lt_u32 s14, 0x100
	s_cselect_b32 s1, s14, s4
	s_ashr_i32 s4, s1, 31
	s_lshr_b32 s4, s4, 24
	s_add_i32 s5, s1, s4
	s_ashr_i32 s4, s5, 8
	s_and_b32 s5, s5, 0xffffff00
	s_sub_i32 s1, s1, s5
	s_ashr_i32 s6, s1, 31
	s_lshr_b32 s6, s6, 28
	s_ashr_i32 s5, s4, 31
	s_add_i32 s6, s1, s6
	s_lshl_b64 s[4:5], s[4:5], 22
	s_ashr_i32 s6, s6, 4
	s_add_u32 s7, s60, s4
	s_addc_u32 s16, s61, s5
	s_lshl_b32 s4, s6, 6
	s_ashr_i32 s5, s4, 31
	s_lshl_b64 s[4:5], s[4:5], 12
	s_add_u32 s7, s7, s4
	s_addc_u32 s16, s16, s5
	s_lshl_b32 s4, s6, 10
	s_lshl_b32 s1, s1, 6
	s_sub_i32 s4, s1, s4
	s_ashr_i32 s5, s4, 31
	s_lshl_b64 s[4:5], s[4:5], 2
	s_add_u32 s4, s7, s4
	s_addc_u32 s5, s16, s5
	v_lshl_add_u64 v[36:37], s[4:5], 0, v[18:19]
	v_lshl_add_u64 v[38:39], v[20:21], 2, v[36:37]
	v_lshl_add_u64 v[40:41], v[22:23], 2, v[36:37]
	v_lshl_add_u64 v[44:45], v[24:25], 2, v[36:37]
	v_lshl_add_u64 v[48:49], v[26:27], 2, v[36:37]
	global_load_dwordx4 v[36:39], v[38:39], off
	s_nop 0
	global_load_dwordx4 v[40:43], v[40:41], off
	s_nop 0
	global_load_dwordx4 v[44:47], v[44:45], off
	s_nop 0
	global_load_dwordx4 v[48:51], v[48:49], off
	s_ashr_i32 s1, s0, 31
	s_lshl_b64 s[6:7], s[0:1], 21
	s_add_u32 s1, s18, s6
	s_addc_u32 s5, s19, s7
	s_lshl_b32 s6, s15, 6
	s_ashr_i32 s7, s6, 31
	s_lshl_b64 s[6:7], s[6:7], 1
	s_add_u32 s6, s1, s6
	s_waitcnt vmcnt(4)
	v_cvt_pk_bf16_f32 v14, v14, s0
	v_cvt_pk_bf16_f32 v15, v15, s0
	v_cvt_pk_bf16_f32 v16, v16, s0
	v_cvt_pk_bf16_f32 v17, v17, s0
	v_cvt_pk_bf16_f32 v10, v10, s0
	v_cvt_pk_bf16_f32 v11, v11, s0
	v_cvt_pk_bf16_f32 v12, v12, s0
	v_cvt_pk_bf16_f32 v13, v13, s0
	v_cvt_pk_bf16_f32 v6, v6, s0
	v_cvt_pk_bf16_f32 v7, v7, s0
	v_cvt_pk_bf16_f32 v8, v8, s0
	v_cvt_pk_bf16_f32 v9, v9, s0
	v_cvt_pk_bf16_f32 v2, v2, s0
	v_cvt_pk_bf16_f32 v3, v3, s0
	v_cvt_pk_bf16_f32 v4, v4, s0
	v_cvt_pk_bf16_f32 v5, v5, s0
	s_addc_u32 s7, s5, s7
	s_lshl_b32 s1, s15, 10
	s_lshl_b32 s0, s0, 14
	s_add_i32 s1, s1, s0
	s_barrier
	ds_write_b16 v1, v14
	ds_write_b16 v1, v15 offset:144
	ds_write_b16 v1, v16 offset:288
	ds_write_b16 v1, v17 offset:432
	ds_write_b16 v1, v10 offset:32
	ds_write_b16 v1, v11 offset:176
	ds_write_b16 v1, v12 offset:320
	ds_write_b16 v1, v13 offset:464
	ds_write_b16 v1, v6 offset:64
	ds_write_b16 v1, v7 offset:208
	ds_write_b16 v1, v8 offset:352
	ds_write_b16 v1, v9 offset:496
	ds_write_b16 v1, v2 offset:96
	ds_write_b16 v1, v3 offset:240
	ds_write_b16 v1, v4 offset:384
	ds_write_b16 v1, v5 offset:528
	s_waitcnt lgkmcnt(0)
	s_barrier
	ds_read_b128 v[2:5], v28
	ds_read_b128 v[6:9], v30
	s_sub_i32 s0, s2, s1
	v_add_u32_e32 v12, s0, v34
	v_add_u32_e32 v14, s0, v29
	v_ashrrev_i32_e32 v13, 31, v12
	v_ashrrev_i32_e32 v15, 31, v14
	v_lshl_add_u64 v[10:11], s[6:7], 0, v[32:33]
	v_lshlrev_b64 v[12:13], 11, v[12:13]
	v_lshlrev_b64 v[14:15], 11, v[14:15]
	s_add_i32 s2, s2, s3
	v_lshl_add_u64 v[12:13], v[10:11], 0, v[12:13]
	v_lshl_add_u64 v[10:11], v[10:11], 0, v[14:15]
	s_mov_b32 s4, s14
	s_cmpk_lt_i32 s14, 0x100
	s_waitcnt lgkmcnt(1)
	global_store_dwordx4 v[12:13], v[2:5], off sc0 sc1
	s_waitcnt lgkmcnt(0)
	global_store_dwordx4 v[10:11], v[6:9], off sc0 sc1
	s_waitcnt vmcnt(5)
	v_mov_b64_e32 v[14:15], v[36:37]
	v_mov_b64_e32 v[16:17], v[38:39]
	s_waitcnt vmcnt(4)
	v_mov_b64_e32 v[10:11], v[40:41]
	v_mov_b64_e32 v[12:13], v[42:43]
	s_waitcnt vmcnt(3)
	v_mov_b64_e32 v[6:7], v[44:45]
	v_mov_b64_e32 v[8:9], v[46:47]
	s_waitcnt vmcnt(2)
	v_mov_b64_e32 v[2:3], v[48:49]
	v_mov_b64_e32 v[4:5], v[50:51]
	s_cbranch_scc1 .LBB0_36

.LBB0_39:
	s_ashr_i32 s0, s14, 31
	s_waitcnt vmcnt(0)
	v_cvt_pk_bf16_f32 v37, v14, s0
	v_cvt_pk_bf16_f32 v42, v15, s0
	v_cvt_pk_bf16_f32 v43, v16, s0
	v_cvt_pk_bf16_f32 v44, v17, s0
	v_cvt_pk_bf16_f32 v45, v10, s0
	v_cvt_pk_bf16_f32 v46, v11, s0
	v_cvt_pk_bf16_f32 v47, v12, s0
	v_cvt_pk_bf16_f32 v48, v13, s0
	v_cvt_pk_bf16_f32 v49, v6, s0
	v_cvt_pk_bf16_f32 v50, v7, s0
	v_cvt_pk_bf16_f32 v51, v8, s0
	v_cvt_pk_bf16_f32 v52, v9, s0
	s_lshr_b32 s0, s0, 25
	s_add_i32 s1, s14, s0
	s_ashr_i32 s0, s1, 7
	s_and_b32 s1, s1, 0xffffff80
	s_sub_i32 s1, s14, s1
	s_ashr_i32 s15, s1, 31
	s_lshr_b32 s15, s15, 29
	s_add_i32 s1, s1, s15
	s_add_i32 s7, s14, s90
	s_ashr_i32 s18, s1, 3
	s_cmpk_lt_u32 s7, 0x1000
	s_cselect_b32 s1, s7, s14
	s_ashr_i32 s14, s1, 31
	s_lshr_b32 s14, s14, 25
	s_add_i32 s15, s1, s14
	s_ashr_i32 s14, s15, 7
	s_and_b32 s15, s15, 0xffffff80
	s_sub_i32 s1, s1, s15
	s_ashr_i32 s16, s1, 31
	s_lshr_b32 s16, s16, 29
	s_ashr_i32 s15, s14, 31
	s_add_i32 s16, s1, s16
	s_lshl_b64 s[14:15], s[14:15], 21
	s_ashr_i32 s16, s16, 3
	s_add_u32 s17, s74, s14
	s_addc_u32 s19, s75, s15
	s_lshl_b32 s14, s16, 6
	s_ashr_i32 s15, s14, 31
	s_lshl_b64 s[14:15], s[14:15], 11
	s_add_u32 s17, s17, s14
	s_addc_u32 s19, s19, s15
	s_lshl_b32 s14, s16, 9
	s_lshl_b32 s1, s1, 6
	s_sub_i32 s14, s1, s14
	s_ashr_i32 s15, s14, 31
	s_lshl_b64 s[14:15], s[14:15], 2
	s_add_u32 s14, s17, s14
	s_addc_u32 s15, s19, s15
	v_lshl_add_u64 v[6:7], s[14:15], 0, v[18:19]
	v_lshl_add_u64 v[8:9], v[20:21], 2, v[6:7]
	v_lshl_add_u64 v[10:11], v[22:23], 2, v[6:7]
	v_lshl_add_u64 v[38:39], v[24:25], 2, v[6:7]
	v_lshl_add_u64 v[40:41], v[26:27], 2, v[6:7]
	global_load_dwordx4 v[14:17], v[8:9], off
	s_nop 0
	global_load_dwordx4 v[10:13], v[10:11], off
	s_nop 0
	global_load_dwordx4 v[6:9], v[38:39], off
	s_nop 0
	global_load_dwordx4 v[38:41], v[40:41], off
	s_ashr_i32 s1, s0, 31
	s_lshl_b64 s[16:17], s[0:1], 20
	s_add_u32 s1, s20, s16
	s_addc_u32 s15, s21, s17
	s_lshl_b32 s16, s18, 6
	s_ashr_i32 s17, s16, 31
	s_lshl_b32 s19, s18, 9
	s_lshl_b64 s[16:17], s[16:17], 1
	s_add_u32 s16, s1, s16
	s_addc_u32 s17, s15, s17
	s_lshl_b32 s15, s0, 13
	v_cvt_pk_bf16_f32 v2, v2, s0
	v_cvt_pk_bf16_f32 v3, v3, s0
	v_cvt_pk_bf16_f32 v4, v4, s0
	v_cvt_pk_bf16_f32 v5, v5, s0
	v_add_u32_e32 v53, s5, v34
	s_add_i32 s0, s19, s15
	v_add_u32_e32 v54, s5, v29
	s_barrier
	ds_write_b16 v1, v37
	ds_write_b16 v1, v42 offset:144
	ds_write_b16 v1, v43 offset:288
	ds_write_b16 v1, v44 offset:432
	ds_write_b16 v1, v45 offset:32
	ds_write_b16 v1, v46 offset:176
	ds_write_b16 v1, v47 offset:320
	ds_write_b16 v1, v48 offset:464
	ds_write_b16 v1, v49 offset:64
	ds_write_b16 v1, v50 offset:208
	ds_write_b16 v1, v51 offset:352
	ds_write_b16 v1, v52 offset:496
	ds_write_b16 v1, v2 offset:96
	ds_write_b16 v1, v3 offset:240
	ds_write_b16 v1, v4 offset:384
	ds_write_b16 v1, v5 offset:528
	v_subrev_u32_e32 v37, s0, v53
	v_subrev_u32_e32 v48, s0, v54
	v_cmp_gt_i32_e32 vcc, s4, v37
	v_cmp_gt_i32_e64 s[0:1], s4, v48
	s_waitcnt lgkmcnt(0)
	v_cndmask_b32_e64 v37, v36, 0, vcc
	v_cndmask_b32_e64 v48, v36, 0, s[0:1]
	v_subrev_u32_e32 v37, s19, v37
	v_subrev_u32_e32 v48, s19, v48
	v_subrev_u32_e32 v37, s15, v37
	v_subrev_u32_e32 v48, s15, v48
	v_add_lshl_u32 v37, v53, v37, 1
	s_barrier
	ds_read_b128 v[2:5], v28
	ds_read_b128 v[42:45], v30
	v_cndmask_b32_e64 v49, 32, 0, vcc
	v_add_lshl_u32 v48, v54, v48, 1
	v_and_b32_e32 v37, 0xffffffc0, v37
	v_cndmask_b32_e64 v50, 32, 0, s[0:1]
	v_and_b32_e32 v51, 0xffffffc0, v48
	v_or3_b32 v48, v49, v31, v37
	v_or3_b32 v50, v50, v35, v51
	v_ashrrev_i32_e32 v49, 31, v48
	v_lshl_add_u64 v[46:47], s[16:17], 0, v[32:33]
	v_ashrrev_i32_e32 v51, 31, v50
	v_lshlrev_b64 v[48:49], 11, v[48:49]
	s_add_i32 s5, s5, s6
	v_lshlrev_b64 v[50:51], 11, v[50:51]
	v_lshl_add_u64 v[48:49], v[46:47], 0, v[48:49]
	s_mov_b32 s14, s7
	s_cmpk_lt_i32 s7, 0x1000
	v_lshl_add_u64 v[46:47], v[46:47], 0, v[50:51]
	s_waitcnt lgkmcnt(1)
	global_store_dwordx4 v[48:49], v[2:5], off sc0 sc1
	s_waitcnt lgkmcnt(0)
	global_store_dwordx4 v[46:47], v[42:45], off sc0 sc1
	s_waitcnt vmcnt(2)
	v_mov_b64_e32 v[2:3], v[38:39]
	v_mov_b64_e32 v[4:5], v[40:41]
	s_cbranch_scc1 .LBB0_39

.LBB0_42:
	s_ashr_i32 s6, s14, 31
	s_lshr_b32 s6, s6, 26
	s_add_i32 s7, s14, s6
	s_ashr_i32 s6, s7, 6
	s_andn2_b32 s7, s7, 63
	s_sub_i32 s7, s14, s7
	s_ashr_i32 s15, s7, 31
	s_lshr_b32 s15, s15, 28
	s_add_i32 s7, s7, s15
	s_add_i32 s18, s14, s90
	s_ashr_i32 s19, s7, 4
	s_cmpk_lt_u32 s18, 0x800
	s_cselect_b32 s7, s18, s14
	s_ashr_i32 s14, s7, 31
	s_lshr_b32 s14, s14, 26
	s_add_i32 s15, s7, s14
	s_ashr_i32 s14, s15, 6
	s_andn2_b32 s15, s15, 63
	s_sub_i32 s7, s7, s15
	s_ashr_i32 s16, s7, 31
	s_lshr_b32 s16, s16, 28
	s_ashr_i32 s15, s14, 31
	s_add_i32 s16, s7, s16
	s_lshl_b64 s[14:15], s[14:15], 20
	s_ashr_i32 s16, s16, 4
	s_add_u32 s17, s80, s14
	s_addc_u32 s20, s81, s15
	s_lshl_b32 s14, s16, 6
	s_ashr_i32 s15, s14, 31
	s_lshl_b64 s[14:15], s[14:15], 12
	s_add_u32 s17, s17, s14
	s_addc_u32 s20, s20, s15
	s_lshl_b32 s14, s16, 10
	s_lshl_b32 s7, s7, 6
	s_sub_i32 s14, s7, s14
	s_ashr_i32 s15, s14, 31
	s_lshl_b64 s[14:15], s[14:15], 2
	s_add_u32 s14, s17, s14
	s_addc_u32 s15, s20, s15
	v_lshl_add_u64 v[36:37], s[14:15], 0, v[18:19]
	v_lshl_add_u64 v[38:39], v[20:21], 2, v[36:37]
	v_lshl_add_u64 v[40:41], v[22:23], 2, v[36:37]
	v_lshl_add_u64 v[44:45], v[24:25], 2, v[36:37]
	v_lshl_add_u64 v[48:49], v[26:27], 2, v[36:37]
	global_load_dwordx4 v[36:39], v[38:39], off
	s_nop 0
	global_load_dwordx4 v[40:43], v[40:41], off
	s_nop 0
	global_load_dwordx4 v[44:47], v[44:45], off
	s_nop 0
	global_load_dwordx4 v[48:51], v[48:49], off
	s_ashr_i32 s7, s6, 31
	s_lshl_b64 s[16:17], s[6:7], 19
	s_add_u32 s7, s22, s16
	s_addc_u32 s15, s23, s17
	s_lshl_b32 s16, s19, 6
	s_ashr_i32 s17, s16, 31
	s_lshl_b64 s[16:17], s[16:17], 1
	s_add_u32 s16, s7, s16
	s_addc_u32 s17, s15, s17
	s_lshl_b32 s7, s19, 10
	s_lshl_b32 s6, s6, 12
	s_waitcnt vmcnt(4)
	v_cvt_pk_bf16_f32 v14, v14, s0
	v_cvt_pk_bf16_f32 v6, v6, s0
	v_cvt_pk_bf16_f32 v7, v7, s0
	v_cvt_pk_bf16_f32 v8, v8, s0
	v_cvt_pk_bf16_f32 v9, v9, s0
	v_cvt_pk_bf16_f32 v2, v2, s0
	v_cvt_pk_bf16_f32 v3, v3, s0
	v_cvt_pk_bf16_f32 v4, v4, s0
	v_cvt_pk_bf16_f32 v5, v5, s0
	s_add_i32 s7, s7, s6
	v_cvt_pk_bf16_f32 v15, v15, s0
	v_cvt_pk_bf16_f32 v16, v16, s0
	v_cvt_pk_bf16_f32 v17, v17, s0
	v_cvt_pk_bf16_f32 v10, v10, s0
	v_cvt_pk_bf16_f32 v11, v11, s0
	v_cvt_pk_bf16_f32 v12, v12, s0
	v_cvt_pk_bf16_f32 v13, v13, s0
	s_waitcnt lgkmcnt(0)
	s_barrier
	ds_write_b16 v1, v14
	ds_write_b16 v1, v15 offset:144
	ds_write_b16 v1, v16 offset:288
	ds_write_b16 v1, v17 offset:432
	ds_write_b16 v1, v10 offset:32
	ds_write_b16 v1, v11 offset:176
	ds_write_b16 v1, v12 offset:320
	ds_write_b16 v1, v13 offset:464
	ds_write_b16 v1, v6 offset:64
	ds_write_b16 v1, v7 offset:208
	ds_write_b16 v1, v8 offset:352
	ds_write_b16 v1, v9 offset:496
	ds_write_b16 v1, v2 offset:96
	ds_write_b16 v1, v3 offset:240
	ds_write_b16 v1, v4 offset:384
	ds_write_b16 v1, v5 offset:528
	s_waitcnt lgkmcnt(0)
	s_barrier
	ds_read_b128 v[2:5], v28
	ds_read_b128 v[6:9], v30
	s_sub_i32 s6, s4, s7
	v_add_u32_e32 v12, s6, v34
	v_add_u32_e32 v14, s6, v29
	v_ashrrev_i32_e32 v13, 31, v12
	v_ashrrev_i32_e32 v15, 31, v14
	v_lshl_add_u64 v[10:11], s[16:17], 0, v[32:33]
	v_lshlrev_b64 v[12:13], 9, v[12:13]
	v_lshlrev_b64 v[14:15], 9, v[14:15]
	s_add_i32 s4, s4, s5
	v_lshl_add_u64 v[12:13], v[10:11], 0, v[12:13]
	v_lshl_add_u64 v[10:11], v[10:11], 0, v[14:15]
	s_mov_b32 s14, s18
	s_cmpk_lt_i32 s18, 0x800
	s_waitcnt lgkmcnt(1)
	global_store_dwordx4 v[12:13], v[2:5], off sc0 sc1
	s_waitcnt lgkmcnt(0)
	global_store_dwordx4 v[10:11], v[6:9], off sc0 sc1
	s_waitcnt vmcnt(5)
	v_mov_b64_e32 v[14:15], v[36:37]
	v_mov_b64_e32 v[16:17], v[38:39]
	s_waitcnt vmcnt(4)
	v_mov_b64_e32 v[10:11], v[40:41]
	v_mov_b64_e32 v[12:13], v[42:43]
	s_waitcnt vmcnt(3)
	v_mov_b64_e32 v[6:7], v[44:45]
	v_mov_b64_e32 v[8:9], v[46:47]
	s_waitcnt vmcnt(2)
	v_mov_b64_e32 v[2:3], v[48:49]
	v_mov_b64_e32 v[4:5], v[50:51]
	s_cbranch_scc1 .LBB0_42

.LBB0_45:
	global_load_dwordx4 v[8:11], v[6:7], off offset:-16
	global_load_dwordx4 v[12:15], v[6:7], off
	v_lshl_add_u64 v[2:3], v[2:3], 0, s[14:15]
	v_cmp_lt_u64_e32 vcc, s[22:23], v[2:3]
	v_lshl_add_u64 v[6:7], v[6:7], 0, s[18:19]
	s_or_b64 s[20:21], vcc, s[20:21]
	s_waitcnt vmcnt(1)
	v_cvt_pk_bf16_f32 v8, v8, v9
	v_cvt_pk_bf16_f32 v9, v10, v11
	s_waitcnt vmcnt(0)
	v_cvt_pk_bf16_f32 v10, v12, v13
	v_cvt_pk_bf16_f32 v11, v14, v15
	global_store_dwordx4 v[4:5], v[8:11], off sc0 sc1
	v_lshl_add_u64 v[4:5], v[4:5], 0, s[16:17]
	s_andn2_b64 exec, exec, s[20:21]
	s_cbranch_execnz .LBB0_45
.LBB0_46:
	s_or_b64 exec, exec, s[6:7]
	v_lshrrev_b32_e32 v1, 20, v0
	v_lshrrev_b32_e32 v0, 10, v0
	v_or_b32_e32 v0, v0, v1
	s_movk_i32 s4, 0x3ff
	v_and_or_b32 v0, v0, s4, v128
	v_cmp_eq_u32_e32 vcc, 0, v0
	s_waitcnt vmcnt(0) lgkmcnt(0)
	s_barrier
	s_and_saveexec_b64 s[6:7], vcc
	s_cbranch_execz .LBB0_56
	s_waitcnt vmcnt(0)
	s_load_dwordx2 s[12:13], s[12:13], 0x58
	v_mov_b32_e32 v2, 0
	s_mov_b64 s[14:15], exec
	v_mbcnt_lo_u32_b32 v1, s14, 0
	v_mbcnt_hi_u32_b32 v1, s15, v1
	s_waitcnt lgkmcnt(0)
	global_load_dword v0, v2, s[12:13] offset:40
	v_cmp_eq_u32_e32 vcc, 0, v1
	s_and_saveexec_b64 s[16:17], vcc
	s_cbranch_execz .LBB0_49
	s_bcnt1_i32_b64 s4, s[14:15]
	v_mov_b32_e32 v3, s4
	global_atomic_add v3, v2, v3, s[12:13] offset:32 sc0

.LBB0_392:
	s_and_b32 s98, s6, 7
	s_lshl_b32 s98, s98, 5
	s_bfe_u32 s99, s6, 0x50005
	s_or_b32 s98, s98, s99
	s_lshl_b32 s98, s98, 3
	s_lshr_b32 s99, s6, 10
	s_lshl_b32 s99, s99, 2
	s_or_b32 s98, s98, s99
	s_bfe_u32 s99, s6, 0x20003
	s_or_b32 s98, s98, s99
	s_ashr_i32 s19, s98, 3
	s_and_b32 s18, s98, 7
	v_lshl_add_u32 v137, s19, 16, v136
	s_andn2_b64 vcc, exec, s[0:1]
	v_lshl_add_u32 v65, s18, 16, v136
	s_cbranch_vccnz .LBB0_394
	v_or_b32_e32 v3, v67, v137
	v_mov_b32_e32 v130, v3
	v_add_u32_e32 v2, 0x4000, v3
	v_lshl_add_u64 v[0:1], v[130:131], 1, s[80:81]
	v_or_b32_e32 v130, v67, v65
	v_add_u32_e32 v10, 0x4000, v130
	v_add_u32_e32 v16, 0x8000, v3
	v_add_u32_e32 v18, 0x8000, v130
	v_add_u32_e32 v24, 0xc000, v3
	v_add_u32_e32 v26, 0xc000, v130
	global_load_dwordx4 v[4:7], v[0:1], off
	v_mov_b32_e32 v3, v131
	v_lshl_add_u64 v[0:1], v[130:131], 1, s[10:11]
	global_load_dwordx4 v[12:15], v[0:1], off
	v_mov_b32_e32 v11, v131
	v_lshl_add_u64 v[0:1], v[2:3], 1, s[80:81]
	global_load_dwordx4 v[20:23], v[0:1], off
	v_mov_b32_e32 v17, v131
	v_lshl_add_u64 v[0:1], v[10:11], 1, s[10:11]
	global_load_dwordx4 v[32:35], v[0:1], off
	v_mov_b32_e32 v19, v131
	v_lshl_add_u64 v[0:1], v[16:17], 1, s[80:81]
	global_load_dwordx4 v[40:43], v[0:1], off
	v_mov_b32_e32 v25, v131
	v_lshl_add_u64 v[0:1], v[18:19], 1, s[10:11]
	global_load_dwordx4 v[48:51], v[0:1], off
	v_mov_b32_e32 v27, v131
	v_lshl_add_u64 v[0:1], v[24:25], 1, s[80:81]
	global_load_dwordx4 v[52:55], v[0:1], off
	v_or_b32_e32 v2, 64, v67
	v_lshl_add_u64 v[0:1], v[26:27], 1, s[10:11]
	global_load_dwordx4 v[60:63], v[0:1], off
	v_or_b32_e32 v0, v2, v137
	v_mov_b32_e32 v1, v131
	v_add_u32_e32 v16, 0x4000, v0
	v_add_u32_e32 v28, 0x8000, v0
	v_add_u32_e32 v44, 0xc000, v0
	v_lshlrev_b32_e32 v3, 1, v66
	v_or_b32_e32 v8, 0x80, v67
	v_or_b32_e32 v10, v2, v65
	v_lshl_add_u64 v[0:1], v[0:1], 1, s[80:81]
	v_lshl_add_u32 v68, v9, 4, v3
	v_or_b32_e32 v69, v8, v137
	v_or_b32_e32 v70, v8, v65
	v_add_u32_e32 v24, 0x4000, v10
	v_add_u32_e32 v36, 0x8000, v10
	s_waitcnt vmcnt(9)
	v_add_u32_e32 v56, 0xc000, v10
	global_load_dwordx4 v[0:3], v[0:1], off
	v_mov_b32_e32 v29, v131
	v_lshl_add_u64 v[8:9], v[10:11], 1, s[10:11]
	global_load_dwordx4 v[8:11], v[8:9], off
	v_mov_b32_e32 v37, v131
	v_lshl_add_u64 v[16:17], v[16:17], 1, s[80:81]
	global_load_dwordx4 v[16:19], v[16:17], off
	v_mov_b32_e32 v45, v131
	v_lshl_add_u64 v[24:25], v[24:25], 1, s[10:11]
	global_load_dwordx4 v[24:27], v[24:25], off
	v_mov_b32_e32 v57, v131
	v_lshl_add_u64 v[28:29], v[28:29], 1, s[80:81]
	global_load_dwordx4 v[28:31], v[28:29], off
	v_mov_b32_e32 v130, v69
	v_lshl_add_u64 v[36:37], v[36:37], 1, s[10:11]
	global_load_dwordx4 v[36:39], v[36:37], off
	v_mov_b32_e32 v138, v67
	v_lshl_add_u64 v[44:45], v[44:45], 1, s[80:81]
	global_load_dwordx4 v[44:47], v[44:45], off
	v_mov_b32_e32 v71, v66
	v_lshl_add_u64 v[56:57], v[56:57], 1, s[10:11]
	global_load_dwordx4 v[56:59], v[56:57], off
	s_barrier
	s_waitcnt vmcnt(15)
	ds_write_b128 v68, v[4:7]
	s_waitcnt vmcnt(14)
	ds_write_b128 v68, v[12:15] offset:20480
	s_waitcnt vmcnt(13)
	ds_write_b128 v68, v[20:23] offset:5120
	s_waitcnt vmcnt(12)
	ds_write_b128 v68, v[32:35] offset:25600
	s_waitcnt vmcnt(11)
	ds_write_b128 v68, v[40:43] offset:10240
	s_waitcnt vmcnt(10)
	ds_write_b128 v68, v[48:51] offset:30720
	s_waitcnt vmcnt(9)
	ds_write_b128 v68, v[52:55] offset:15360
	s_waitcnt vmcnt(8)
	ds_write_b128 v68, v[60:63] offset:35840
	v_add_u32_e32 v68, 0xa00, v66
	v_lshl_add_u64 v[4:5], v[130:131], 1, s[80:81]
	v_mov_b32_e32 v130, v70
	global_load_dwordx4 v[4:7], v[4:5], off
	s_waitcnt vmcnt(7)
	v_mov_b32_e32 v132, v9
	v_lshl_add_u64 v[12:13], v[130:131], 1, s[10:11]
	v_add_u32_e32 v130, 0x4000, v69
	global_load_dwordx4 v[12:15], v[12:13], off
	v_mov_b32_e32 v133, v10
	v_lshl_add_u64 v[20:21], v[130:131], 1, s[80:81]
	v_add_u32_e32 v130, 0x4000, v70
	global_load_dwordx4 v[20:23], v[20:21], off
	s_nop 0
	v_lshl_add_u64 v[32:33], v[130:131], 1, s[10:11]
	v_add_u32_e32 v130, 0x8000, v69
	global_load_dwordx4 v[32:35], v[32:33], off
	s_nop 0
	v_lshl_add_u64 v[40:41], v[130:131], 1, s[80:81]
	v_add_u32_e32 v130, 0x8000, v70
	global_load_dwordx4 v[40:43], v[40:41], off
	s_nop 0
	v_lshl_add_u64 v[48:49], v[130:131], 1, s[10:11]
	v_add_u32_e32 v130, 0xc000, v69
	global_load_dwordx4 v[48:51], v[48:49], off
	v_add_u32_e32 v69, 0x1400, v66
	v_lshl_add_u64 v[52:53], v[130:131], 1, s[80:81]
	v_add_u32_e32 v130, 0xc000, v70
	global_load_dwordx4 v[52:55], v[52:53], off
	v_add_u32_e32 v70, 0x1e00, v66
	v_lshl_add_u64 v[60:61], v[130:131], 1, s[10:11]
	global_load_dwordx4 v[60:63], v[60:61], off
.LBB0_394:
	s_and_b32 s98, s17, 7
	s_lshl_b32 s98, s98, 5
	s_bfe_u32 s99, s17, 0x50005
	s_or_b32 s98, s98, s99
	s_lshl_b32 s98, s98, 3
	s_lshr_b32 s99, s17, 10
	s_lshl_b32 s99, s99, 2
	s_or_b32 s98, s98, s99
	s_bfe_u32 s99, s17, 0x20003
	s_or_b32 s98, s98, s99
	s_and_b32 s0, s98, 7
	s_add_i32 s20, s6, s90
	s_cmpk_gt_i32 s20, 0x7ff
	v_lshl_add_u32 v142, s0, 16, v136
	s_cselect_b64 s[0:1], -1, 0
	s_cmpk_lt_i32 s20, 0x800
	s_cselect_b64 s[2:3], -1, 0
	s_and_b64 s[4:5], s[2:3], exec
	v_lshlrev_b32_e32 v10, 1, v138
	s_cselect_b32 s4, s20, s6
	s_and_b32 s98, s4, 7
	s_lshl_b32 s98, s98, 5
	s_bfe_u32 s99, s4, 0x50005
	s_or_b32 s98, s98, s99
	s_lshl_b32 s98, s98, 3
	s_lshr_b32 s99, s4, 10
	s_lshl_b32 s99, s99, 2
	s_or_b32 s98, s98, s99
	s_bfe_u32 s99, s4, 0x20003
	s_or_b32 s4, s98, s99
	v_bfe_u32 v139, v64, 6, 1
	v_and_b32_e32 v9, 15, v64
	v_lshl_add_u32 v145, v71, 1, v10
	v_lshl_add_u32 v146, v68, 1, v10
	v_lshl_add_u32 v147, v69, 1, v10
	v_lshl_add_u32 v148, v70, 1, v10
	v_ashrrev_i32_e32 v10, 1, v64
	s_lshl_b32 s5, s4, 4
	s_lshl_b32 s4, s4, 7
	v_bfe_u32 v140, v64, 4, 2
	v_and_or_b32 v141, v10, s15, v9
	v_lshl_or_b32 v9, v139, 6, v9
	s_and_b32 s5, s5, 0x7fff80
	s_and_b32 s4, s4, 0x380
	v_lshlrev_b32_e32 v10, 4, v140
	v_mul_u32_u24_e32 v9, 0x50, v9
	v_add_lshl_u32 v143, s5, v129, 9
	v_add_lshl_u32 v144, s4, v129, 9
	v_mad_u64_u32 v[134:135], s[4:5], v141, s16, v[10:11]
	v_lshlrev_b32_e32 v9, 1, v9
	v_or_b32_e32 v66, 0x1c0, v138
	v_add_u32_e32 v135, v10, v9
	v_or_b32_e32 v64, 0xf000, v10
	v_add_u32_e32 v67, 0x1400, v9
	v_add_u32_e32 v9, 0x1e00, v9
	v_add_u32_e32 v149, v64, v67
	v_add_u32_e32 v150, v64, v9
	v_or_b32_e32 v10, 0xf040, v10
	v_add_u32_e32 v153, v66, v137
	v_add_u32_e32 v154, v66, v65
	v_mov_b32_e32 v64, 0
	v_add_u32_e32 v151, v10, v67
	v_add_u32_e32 v152, v10, v9
	v_add_u32_e32 v155, 0x4000, v153
	v_add_u32_e32 v156, 0x4000, v154
	v_add_u32_e32 v157, 0x8000, v153
	v_add_u32_e32 v158, 0x8000, v154
	v_add_u32_e32 v159, 0xc000, v153
	v_add_u32_e32 v160, 0xc000, v154
	s_mov_b32 s21, 0
	v_mov_b32_e32 v65, v64
	v_mov_b32_e32 v66, v64
	v_mov_b32_e32 v67, v64
	v_mov_b32_e32 v72, v64
	v_mov_b32_e32 v73, v64
	v_mov_b32_e32 v74, v64
	v_mov_b32_e32 v75, v64
	v_mov_b32_e32 v80, v64
	v_mov_b32_e32 v81, v64
	v_mov_b32_e32 v82, v64
	v_mov_b32_e32 v83, v64
	v_mov_b32_e32 v88, v64
	v_mov_b32_e32 v89, v64
	v_mov_b32_e32 v90, v64
	v_mov_b32_e32 v91, v64
	v_mov_b32_e32 v96, v64
	v_mov_b32_e32 v97, v64
	v_mov_b32_e32 v98, v64
	v_mov_b32_e32 v99, v64
	v_mov_b32_e32 v104, v64
	v_mov_b32_e32 v105, v64
	v_mov_b32_e32 v106, v64
	v_mov_b32_e32 v107, v64
	v_mov_b32_e32 v112, v64
	v_mov_b32_e32 v113, v64
	v_mov_b32_e32 v114, v64
	v_mov_b32_e32 v115, v64
	v_mov_b32_e32 v120, v64
	v_mov_b32_e32 v121, v64
	v_mov_b32_e32 v122, v64
	v_mov_b32_e32 v123, v64
	v_mov_b32_e32 v68, v64
	v_mov_b32_e32 v69, v64
	v_mov_b32_e32 v70, v64
	v_mov_b32_e32 v71, v64
	v_mov_b32_e32 v76, v64
	v_mov_b32_e32 v77, v64
	v_mov_b32_e32 v78, v64
	v_mov_b32_e32 v79, v64
	v_mov_b32_e32 v84, v64
	v_mov_b32_e32 v85, v64
	v_mov_b32_e32 v86, v64
	v_mov_b32_e32 v87, v64
	v_mov_b32_e32 v92, v64
	v_mov_b32_e32 v93, v64
	v_mov_b32_e32 v94, v64
	v_mov_b32_e32 v95, v64
	v_mov_b32_e32 v100, v64
	v_mov_b32_e32 v101, v64
	v_mov_b32_e32 v102, v64
	v_mov_b32_e32 v103, v64
	v_mov_b32_e32 v108, v64
	v_mov_b32_e32 v109, v64
	v_mov_b32_e32 v110, v64
	v_mov_b32_e32 v111, v64
	v_mov_b32_e32 v116, v64
	v_mov_b32_e32 v117, v64
	v_mov_b32_e32 v118, v64
	v_mov_b32_e32 v119, v64
	v_mov_b32_e32 v124, v64
	v_mov_b32_e32 v125, v64
	v_mov_b32_e32 v126, v64
	v_mov_b32_e32 v127, v64
	v_mov_b32_e32 v9, v132
	v_mov_b32_e32 v10, v133
	s_branch .LBB0_396

.LBB0_471:
	s_and_b32 s98, s6, 7
	s_lshl_b32 s98, s98, 5
	s_bfe_u32 s99, s6, 0x50005
	s_or_b32 s98, s98, s99
	s_lshl_b32 s98, s98, 3
	s_lshr_b32 s99, s6, 10
	s_lshl_b32 s99, s99, 2
	s_or_b32 s98, s98, s99
	s_bfe_u32 s99, s6, 0x20003
	s_or_b32 s98, s98, s99
	s_ashr_i32 s17, s98, 3
	s_and_b32 s16, s98, 7
	v_lshl_add_u32 v138, s17, 17, v136
	s_andn2_b64 vcc, exec, s[0:1]
	v_lshl_add_u32 v64, s16, 17, v136
	s_cbranch_vccnz .LBB0_473
	v_or_b32_e32 v3, v66, v138
	v_mov_b32_e32 v130, v3
	v_add_u32_e32 v2, 0x8000, v3
	v_lshl_add_u64 v[0:1], v[130:131], 1, s[78:79]
	v_or_b32_e32 v130, v66, v64
	v_add_u32_e32 v10, 0x8000, v130
	v_add_u32_e32 v16, 0x10000, v3
	v_add_u32_e32 v18, 0x10000, v130
	v_add_u32_e32 v24, 0x18000, v3
	v_add_u32_e32 v26, 0x18000, v130
	global_load_dwordx4 v[4:7], v[0:1], off
	v_mov_b32_e32 v3, v131
	v_lshl_add_u64 v[0:1], v[130:131], 1, s[8:9]
	global_load_dwordx4 v[12:15], v[0:1], off
	v_mov_b32_e32 v11, v131
	v_lshl_add_u64 v[0:1], v[2:3], 1, s[78:79]
	global_load_dwordx4 v[20:23], v[0:1], off
	v_mov_b32_e32 v17, v131
	v_lshl_add_u64 v[0:1], v[10:11], 1, s[8:9]
	global_load_dwordx4 v[32:35], v[0:1], off
	v_mov_b32_e32 v19, v131
	v_lshl_add_u64 v[0:1], v[16:17], 1, s[78:79]
	global_load_dwordx4 v[40:43], v[0:1], off
	v_mov_b32_e32 v25, v131
	v_lshl_add_u64 v[0:1], v[18:19], 1, s[8:9]
	global_load_dwordx4 v[48:51], v[0:1], off
	v_mov_b32_e32 v27, v131
	v_lshl_add_u64 v[0:1], v[24:25], 1, s[78:79]
	global_load_dwordx4 v[52:55], v[0:1], off
	v_or_b32_e32 v2, 64, v66
	v_lshl_add_u64 v[0:1], v[26:27], 1, s[8:9]
	global_load_dwordx4 v[60:63], v[0:1], off
	v_or_b32_e32 v0, v2, v138
	v_mov_b32_e32 v1, v131
	v_add_u32_e32 v16, 0x8000, v0
	v_add_u32_e32 v28, 0x10000, v0
	v_add_u32_e32 v44, 0x18000, v0
	v_lshlrev_b32_e32 v3, 1, v65
	v_or_b32_e32 v8, 0x80, v66
	v_or_b32_e32 v10, v2, v64
	v_lshl_add_u64 v[0:1], v[0:1], 1, s[78:79]
	v_lshl_add_u32 v67, v9, 4, v3
	v_or_b32_e32 v68, v8, v138
	v_or_b32_e32 v69, v8, v64
	v_add_u32_e32 v24, 0x8000, v10
	v_add_u32_e32 v36, 0x10000, v10
	s_waitcnt vmcnt(9)
	v_add_u32_e32 v56, 0x18000, v10
	global_load_dwordx4 v[0:3], v[0:1], off
	v_mov_b32_e32 v29, v131
	v_lshl_add_u64 v[8:9], v[10:11], 1, s[8:9]
	global_load_dwordx4 v[8:11], v[8:9], off
	v_mov_b32_e32 v37, v131
	v_lshl_add_u64 v[16:17], v[16:17], 1, s[78:79]
	global_load_dwordx4 v[16:19], v[16:17], off
	v_mov_b32_e32 v45, v131
	v_lshl_add_u64 v[24:25], v[24:25], 1, s[8:9]
	global_load_dwordx4 v[24:27], v[24:25], off
	v_mov_b32_e32 v57, v131
	v_lshl_add_u64 v[28:29], v[28:29], 1, s[78:79]
	global_load_dwordx4 v[28:31], v[28:29], off
	v_mov_b32_e32 v130, v68
	v_lshl_add_u64 v[36:37], v[36:37], 1, s[8:9]
	global_load_dwordx4 v[36:39], v[36:37], off
	v_mov_b32_e32 v139, v66
	v_lshl_add_u64 v[44:45], v[44:45], 1, s[78:79]
	global_load_dwordx4 v[44:47], v[44:45], off
	v_mov_b32_e32 v70, v65
	v_lshl_add_u64 v[56:57], v[56:57], 1, s[8:9]
	global_load_dwordx4 v[56:59], v[56:57], off
	s_barrier
	s_waitcnt vmcnt(15)
	ds_write_b128 v67, v[4:7]
	s_waitcnt vmcnt(14)
	ds_write_b128 v67, v[12:15] offset:20480
	s_waitcnt vmcnt(13)
	ds_write_b128 v67, v[20:23] offset:5120
	s_waitcnt vmcnt(12)
	ds_write_b128 v67, v[32:35] offset:25600
	s_waitcnt vmcnt(11)
	ds_write_b128 v67, v[40:43] offset:10240
	s_waitcnt vmcnt(10)
	ds_write_b128 v67, v[48:51] offset:30720
	s_waitcnt vmcnt(9)
	ds_write_b128 v67, v[52:55] offset:15360
	s_waitcnt vmcnt(8)
	ds_write_b128 v67, v[60:63] offset:35840
	v_add_u32_e32 v67, 0xa00, v65
	v_lshl_add_u64 v[4:5], v[130:131], 1, s[78:79]
	v_mov_b32_e32 v130, v69
	global_load_dwordx4 v[4:7], v[4:5], off
	s_waitcnt vmcnt(7)
	v_mov_b32_e32 v132, v9
	v_lshl_add_u64 v[12:13], v[130:131], 1, s[8:9]
	v_add_u32_e32 v130, 0x8000, v68
	global_load_dwordx4 v[12:15], v[12:13], off
	v_mov_b32_e32 v133, v10
	v_lshl_add_u64 v[20:21], v[130:131], 1, s[78:79]
	v_add_u32_e32 v130, 0x8000, v69
	global_load_dwordx4 v[20:23], v[20:21], off
	s_nop 0
	v_lshl_add_u64 v[32:33], v[130:131], 1, s[8:9]
	v_add_u32_e32 v130, 0x10000, v68
	global_load_dwordx4 v[32:35], v[32:33], off
	s_nop 0
	v_lshl_add_u64 v[40:41], v[130:131], 1, s[78:79]
	v_add_u32_e32 v130, 0x10000, v69
	global_load_dwordx4 v[40:43], v[40:41], off
	s_nop 0
	v_lshl_add_u64 v[48:49], v[130:131], 1, s[8:9]
	v_add_u32_e32 v130, 0x18000, v68
	global_load_dwordx4 v[48:51], v[48:49], off
	v_add_u32_e32 v68, 0x1400, v65
	v_lshl_add_u64 v[52:53], v[130:131], 1, s[78:79]
	v_add_u32_e32 v130, 0x18000, v69
	global_load_dwordx4 v[52:55], v[52:53], off
	v_add_u32_e32 v69, 0x1e00, v65
	v_lshl_add_u64 v[60:61], v[130:131], 1, s[8:9]
	global_load_dwordx4 v[60:63], v[60:61], off
.LBB0_473:
	s_and_b32 s98, s15, 7
	s_lshl_b32 s98, s98, 5
	s_bfe_u32 s99, s15, 0x50005
	s_or_b32 s98, s98, s99
	s_lshl_b32 s98, s98, 3
	s_lshr_b32 s99, s15, 10
	s_lshl_b32 s99, s99, 2
	s_or_b32 s98, s98, s99
	s_bfe_u32 s99, s15, 0x20003
	s_or_b32 s98, s98, s99
	s_and_b32 s0, s98, 7
	s_add_i32 s18, s6, s90
	s_cmpk_gt_i32 s18, 0x7ff
	v_lshl_add_u32 v140, s0, 17, v136
	s_cselect_b64 s[0:1], -1, 0
	s_cmpk_lt_i32 s18, 0x800
	s_cselect_b64 s[2:3], -1, 0
	s_and_b64 s[4:5], s[2:3], exec
	s_cselect_b32 s4, s18, s6
	s_and_b32 s98, s4, 7
	s_lshl_b32 s98, s98, 5
	s_bfe_u32 s99, s4, 0x50005
	s_or_b32 s98, s98, s99
	s_lshl_b32 s98, s98, 3
	s_lshr_b32 s99, s4, 10
	s_lshl_b32 s99, s99, 2
	s_or_b32 s98, s98, s99
	s_bfe_u32 s99, s4, 0x20003
	s_or_b32 s4, s98, s99
	v_lshlrev_b32_e32 v10, 1, v139
	s_lshl_b32 s5, s4, 4
	s_lshl_b32 s4, s4, 7
	v_and_b32_e32 v9, 15, v137
	v_bfe_u32 v141, v137, 4, 2
	v_lshl_add_u32 v144, v70, 1, v10
	v_lshl_add_u32 v145, v67, 1, v10
	v_lshl_add_u32 v146, v68, 1, v10
	v_lshl_add_u32 v147, v69, 1, v10
	v_ashrrev_i32_e32 v10, 1, v137
	s_and_b32 s5, s5, 0x3fff80
	s_and_b32 s4, s4, 0x380
	v_and_or_b32 v148, v10, s13, v9
	v_lshlrev_b32_e32 v10, 4, v141
	v_and_b32_e32 v9, 0x4f, v137
	v_add_lshl_u32 v142, s5, v129, 10
	v_add_lshl_u32 v143, s4, v129, 10
	v_or_b32_e32 v65, 0x3c0, v139
	v_mad_u64_u32 v[134:135], s[4:5], v148, s14, v[10:11]
	v_mul_u32_u24_e32 v9, 0x50, v9
	v_lshl_add_u32 v135, v9, 1, v10
	v_add_u32_e32 v151, v65, v138
	v_add_u32_e32 v152, v65, v64
	v_mov_b32_e32 v64, 0
	v_add_u32_e32 v149, 0xf000, v135
	v_add_u32_e32 v150, 0xf040, v135
	v_add_u32_e32 v153, 0x8000, v151
	v_add_u32_e32 v154, 0x8000, v152
	v_add_u32_e32 v155, 0x10000, v151
	v_add_u32_e32 v156, 0x10000, v152
	v_add_u32_e32 v157, 0x18000, v151
	v_add_u32_e32 v158, 0x18000, v152
	s_mov_b32 s19, 0
	v_mov_b32_e32 v65, v64
	v_mov_b32_e32 v66, v64
	v_mov_b32_e32 v67, v64
	v_mov_b32_e32 v68, v64
	v_mov_b32_e32 v69, v64
	v_mov_b32_e32 v70, v64
	v_mov_b32_e32 v71, v64
	v_mov_b32_e32 v72, v64
	v_mov_b32_e32 v73, v64
	v_mov_b32_e32 v74, v64
	v_mov_b32_e32 v75, v64
	v_mov_b32_e32 v76, v64
	v_mov_b32_e32 v77, v64
	v_mov_b32_e32 v78, v64
	v_mov_b32_e32 v79, v64
	v_mov_b32_e32 v80, v64
	v_mov_b32_e32 v81, v64
	v_mov_b32_e32 v82, v64
	v_mov_b32_e32 v83, v64
	v_mov_b32_e32 v84, v64
	v_mov_b32_e32 v85, v64
	v_mov_b32_e32 v86, v64
	v_mov_b32_e32 v87, v64
	v_mov_b32_e32 v88, v64
	v_mov_b32_e32 v89, v64
	v_mov_b32_e32 v90, v64
	v_mov_b32_e32 v91, v64
	v_mov_b32_e32 v92, v64
	v_mov_b32_e32 v93, v64
	v_mov_b32_e32 v94, v64
	v_mov_b32_e32 v95, v64
	v_mov_b32_e32 v96, v64
	v_mov_b32_e32 v97, v64
	v_mov_b32_e32 v98, v64
	v_mov_b32_e32 v99, v64
	v_mov_b32_e32 v100, v64
	v_mov_b32_e32 v101, v64
	v_mov_b32_e32 v102, v64
	v_mov_b32_e32 v103, v64
	v_mov_b32_e32 v104, v64
	v_mov_b32_e32 v105, v64
	v_mov_b32_e32 v106, v64
	v_mov_b32_e32 v107, v64
	v_mov_b32_e32 v108, v64
	v_mov_b32_e32 v109, v64
	v_mov_b32_e32 v110, v64
	v_mov_b32_e32 v111, v64
	v_mov_b32_e32 v112, v64
	v_mov_b32_e32 v113, v64
	v_mov_b32_e32 v114, v64
	v_mov_b32_e32 v115, v64
	v_mov_b32_e32 v116, v64
	v_mov_b32_e32 v117, v64
	v_mov_b32_e32 v118, v64
	v_mov_b32_e32 v119, v64
	v_mov_b32_e32 v120, v64
	v_mov_b32_e32 v121, v64
	v_mov_b32_e32 v122, v64
	v_mov_b32_e32 v123, v64
	v_mov_b32_e32 v124, v64
	v_mov_b32_e32 v125, v64
	v_mov_b32_e32 v126, v64
	v_mov_b32_e32 v127, v64
	v_mov_b32_e32 v9, v132
	v_mov_b32_e32 v10, v133
	s_branch .LBB0_475

.LBB0_1595:
	s_and_b32 s98, s4, 7
	s_lshl_b32 s98, s98, 5
	s_bfe_u32 s99, s4, 0x50005
	s_or_b32 s98, s98, s99
	s_lshl_b32 s98, s98, 3
	s_lshr_b32 s99, s4, 10
	s_lshl_b32 s99, s99, 2
	s_or_b32 s98, s98, s99
	s_bfe_u32 s99, s4, 0x20003
	s_or_b32 s98, s98, s99
	s_ashr_i32 s13, s98, 3
	s_and_b32 s12, s98, 7
	v_lshl_add_u32 v138, s13, 17, v136
	s_andn2_b64 vcc, exec, s[0:1]
	v_lshl_add_u32 v64, s12, 17, v136
	s_cbranch_vccnz .LBB0_1597
	v_or_b32_e32 v3, v66, v138
	v_mov_b32_e32 v130, v3
	v_add_u32_e32 v2, 0x8000, v3
	v_lshl_add_u64 v[0:1], v[130:131], 1, s[78:79]
	v_or_b32_e32 v130, v66, v64
	v_add_u32_e32 v10, 0x8000, v130
	v_add_u32_e32 v16, 0x10000, v3
	v_add_u32_e32 v18, 0x10000, v130
	v_add_u32_e32 v24, 0x18000, v3
	v_add_u32_e32 v26, 0x18000, v130
	global_load_dwordx4 v[4:7], v[0:1], off
	v_mov_b32_e32 v3, v131
	v_lshl_add_u64 v[0:1], v[130:131], 1, s[84:85]
	global_load_dwordx4 v[12:15], v[0:1], off
	v_mov_b32_e32 v11, v131
	v_lshl_add_u64 v[0:1], v[2:3], 1, s[78:79]
	global_load_dwordx4 v[20:23], v[0:1], off
	v_mov_b32_e32 v17, v131
	v_lshl_add_u64 v[0:1], v[10:11], 1, s[84:85]
	global_load_dwordx4 v[32:35], v[0:1], off
	v_mov_b32_e32 v19, v131
	v_lshl_add_u64 v[0:1], v[16:17], 1, s[78:79]
	global_load_dwordx4 v[40:43], v[0:1], off
	v_mov_b32_e32 v25, v131
	v_lshl_add_u64 v[0:1], v[18:19], 1, s[84:85]
	global_load_dwordx4 v[48:51], v[0:1], off
	v_mov_b32_e32 v27, v131
	v_lshl_add_u64 v[0:1], v[24:25], 1, s[78:79]
	global_load_dwordx4 v[52:55], v[0:1], off
	v_or_b32_e32 v2, 64, v66
	v_lshl_add_u64 v[0:1], v[26:27], 1, s[84:85]
	global_load_dwordx4 v[60:63], v[0:1], off
	v_or_b32_e32 v0, v2, v138
	v_mov_b32_e32 v1, v131
	v_add_u32_e32 v16, 0x8000, v0
	v_add_u32_e32 v28, 0x10000, v0
	v_add_u32_e32 v44, 0x18000, v0
	v_lshlrev_b32_e32 v3, 1, v65
	v_or_b32_e32 v8, 0x80, v66
	v_or_b32_e32 v10, v2, v64
	v_lshl_add_u64 v[0:1], v[0:1], 1, s[78:79]
	v_lshl_add_u32 v67, v9, 4, v3
	v_or_b32_e32 v68, v8, v138
	v_or_b32_e32 v69, v8, v64
	v_add_u32_e32 v24, 0x8000, v10
	v_add_u32_e32 v36, 0x10000, v10
	s_waitcnt vmcnt(25)
	v_add_u32_e32 v56, 0x18000, v10
	global_load_dwordx4 v[0:3], v[0:1], off
	v_mov_b32_e32 v29, v131
	v_lshl_add_u64 v[8:9], v[10:11], 1, s[84:85]
	global_load_dwordx4 v[8:11], v[8:9], off
	v_mov_b32_e32 v37, v131
	v_lshl_add_u64 v[16:17], v[16:17], 1, s[78:79]
	global_load_dwordx4 v[16:19], v[16:17], off
	v_mov_b32_e32 v45, v131
	v_lshl_add_u64 v[24:25], v[24:25], 1, s[84:85]
	global_load_dwordx4 v[24:27], v[24:25], off
	v_mov_b32_e32 v57, v131
	v_lshl_add_u64 v[28:29], v[28:29], 1, s[78:79]
	global_load_dwordx4 v[28:31], v[28:29], off
	v_mov_b32_e32 v130, v68
	v_lshl_add_u64 v[36:37], v[36:37], 1, s[84:85]
	global_load_dwordx4 v[36:39], v[36:37], off
	v_mov_b32_e32 v139, v66
	v_lshl_add_u64 v[44:45], v[44:45], 1, s[78:79]
	global_load_dwordx4 v[44:47], v[44:45], off
	v_mov_b32_e32 v70, v65
	v_lshl_add_u64 v[56:57], v[56:57], 1, s[84:85]
	global_load_dwordx4 v[56:59], v[56:57], off
	s_barrier
	s_waitcnt vmcnt(15)
	ds_write_b128 v67, v[4:7]
	s_waitcnt vmcnt(14)
	ds_write_b128 v67, v[12:15] offset:20480
	s_waitcnt vmcnt(13)
	ds_write_b128 v67, v[20:23] offset:5120
	s_waitcnt vmcnt(12)
	ds_write_b128 v67, v[32:35] offset:25600
	s_waitcnt vmcnt(11)
	ds_write_b128 v67, v[40:43] offset:10240
	s_waitcnt vmcnt(10)
	ds_write_b128 v67, v[48:51] offset:30720
	s_waitcnt vmcnt(9)
	ds_write_b128 v67, v[52:55] offset:15360
	s_waitcnt vmcnt(8)
	ds_write_b128 v67, v[60:63] offset:35840
	v_add_u32_e32 v67, 0xa00, v65
	v_lshl_add_u64 v[4:5], v[130:131], 1, s[78:79]
	v_mov_b32_e32 v130, v69
	global_load_dwordx4 v[4:7], v[4:5], off
	s_waitcnt vmcnt(7)
	v_mov_b32_e32 v132, v9
	v_lshl_add_u64 v[12:13], v[130:131], 1, s[84:85]
	v_add_u32_e32 v130, 0x8000, v68
	global_load_dwordx4 v[12:15], v[12:13], off
	v_mov_b32_e32 v133, v10
	v_lshl_add_u64 v[20:21], v[130:131], 1, s[78:79]
	v_add_u32_e32 v130, 0x8000, v69
	global_load_dwordx4 v[20:23], v[20:21], off
	s_nop 0
	v_lshl_add_u64 v[32:33], v[130:131], 1, s[84:85]
	v_add_u32_e32 v130, 0x10000, v68
	global_load_dwordx4 v[32:35], v[32:33], off
	s_nop 0
	v_lshl_add_u64 v[40:41], v[130:131], 1, s[78:79]
	v_add_u32_e32 v130, 0x10000, v69
	global_load_dwordx4 v[40:43], v[40:41], off
	s_nop 0
	v_lshl_add_u64 v[48:49], v[130:131], 1, s[84:85]
	v_add_u32_e32 v130, 0x18000, v68
	global_load_dwordx4 v[48:51], v[48:49], off
	v_add_u32_e32 v68, 0x1400, v65
	v_lshl_add_u64 v[52:53], v[130:131], 1, s[78:79]
	v_add_u32_e32 v130, 0x18000, v69
	global_load_dwordx4 v[52:55], v[52:53], off
	v_add_u32_e32 v69, 0x1e00, v65
	v_lshl_add_u64 v[60:61], v[130:131], 1, s[84:85]
	global_load_dwordx4 v[60:63], v[60:61], off
.LBB0_1597:
	s_and_b32 s98, s11, 7
	s_lshl_b32 s98, s98, 5
	s_bfe_u32 s99, s11, 0x50005
	s_or_b32 s98, s98, s99
	s_lshl_b32 s98, s98, 3
	s_lshr_b32 s99, s11, 10
	s_lshl_b32 s99, s99, 2
	s_or_b32 s98, s98, s99
	s_bfe_u32 s99, s11, 0x20003
	s_or_b32 s98, s98, s99
	s_and_b32 s0, s98, 7
	v_lshl_add_u32 v140, s0, 17, v136
	v_readlane_b32 s0, v237, 56
	v_readlane_b32 s2, v237, 58
	s_add_i32 s14, s4, s2
	v_readlane_b32 s1, v237, 57
	s_cmpk_gt_i32 s14, 0x7ff
	v_readlane_b32 s3, v237, 59
	s_cselect_b64 s[0:1], -1, 0
	s_cmpk_lt_i32 s14, 0x800
	s_cselect_b64 s[2:3], -1, 0
	s_and_b64 s[6:7], s[2:3], exec
	s_cselect_b32 s4, s14, s4
	s_and_b32 s98, s4, 7
	s_lshl_b32 s98, s98, 5
	s_bfe_u32 s99, s4, 0x50005
	s_or_b32 s98, s98, s99
	s_lshl_b32 s98, s98, 3
	s_lshr_b32 s99, s4, 10
	s_lshl_b32 s99, s99, 2
	s_or_b32 s98, s98, s99
	s_bfe_u32 s99, s4, 0x20003
	s_or_b32 s4, s98, s99
	v_lshlrev_b32_e32 v10, 1, v139
	s_lshl_b32 s5, s4, 4
	s_lshl_b32 s4, s4, 7
	v_and_b32_e32 v9, 15, v137
	v_bfe_u32 v141, v137, 4, 2
	v_lshl_add_u32 v144, v70, 1, v10
	v_lshl_add_u32 v145, v67, 1, v10
	v_lshl_add_u32 v146, v68, 1, v10
	v_lshl_add_u32 v147, v69, 1, v10
	v_ashrrev_i32_e32 v10, 1, v137
	s_and_b32 s5, s5, 0x3fff80
	s_and_b32 s4, s4, 0x380
	v_and_or_b32 v148, v10, s9, v9
	v_lshlrev_b32_e32 v10, 4, v141
	v_and_b32_e32 v9, 0x4f, v137
	v_add_lshl_u32 v142, s5, v129, 10
	v_add_lshl_u32 v143, s4, v129, 10
	v_or_b32_e32 v65, 0x3c0, v139
	v_mad_u64_u32 v[134:135], s[4:5], v148, s10, v[10:11]
	v_mul_u32_u24_e32 v9, 0x50, v9
	v_lshl_add_u32 v135, v9, 1, v10
	v_add_u32_e32 v151, v65, v138
	v_add_u32_e32 v152, v65, v64
	v_mov_b32_e32 v64, 0
	v_add_u32_e32 v149, 0xf000, v135
	v_add_u32_e32 v150, 0xf040, v135
	v_add_u32_e32 v153, 0x8000, v151
	v_add_u32_e32 v154, 0x8000, v152
	v_add_u32_e32 v155, 0x10000, v151
	v_add_u32_e32 v156, 0x10000, v152
	v_add_u32_e32 v157, 0x18000, v151
	v_add_u32_e32 v158, 0x18000, v152
	s_mov_b32 s15, 0
	v_mov_b32_e32 v65, v64
	v_mov_b32_e32 v66, v64
	v_mov_b32_e32 v67, v64
	v_mov_b32_e32 v68, v64
	v_mov_b32_e32 v69, v64
	v_mov_b32_e32 v70, v64
	v_mov_b32_e32 v71, v64
	v_mov_b32_e32 v72, v64
	v_mov_b32_e32 v73, v64
	v_mov_b32_e32 v74, v64
	v_mov_b32_e32 v75, v64
	v_mov_b32_e32 v76, v64
	v_mov_b32_e32 v77, v64
	v_mov_b32_e32 v78, v64
	v_mov_b32_e32 v79, v64
	v_mov_b32_e32 v80, v64
	v_mov_b32_e32 v81, v64
	v_mov_b32_e32 v82, v64
	v_mov_b32_e32 v83, v64
	v_mov_b32_e32 v84, v64
	v_mov_b32_e32 v85, v64
	v_mov_b32_e32 v86, v64
	v_mov_b32_e32 v87, v64
	v_mov_b32_e32 v88, v64
	v_mov_b32_e32 v89, v64
	v_mov_b32_e32 v90, v64
	v_mov_b32_e32 v91, v64
	v_mov_b32_e32 v92, v64
	v_mov_b32_e32 v93, v64
	v_mov_b32_e32 v94, v64
	v_mov_b32_e32 v95, v64
	v_mov_b32_e32 v96, v64
	v_mov_b32_e32 v97, v64
	v_mov_b32_e32 v98, v64
	v_mov_b32_e32 v99, v64
	v_mov_b32_e32 v100, v64
	v_mov_b32_e32 v101, v64
	v_mov_b32_e32 v102, v64
	v_mov_b32_e32 v103, v64
	v_mov_b32_e32 v104, v64
	v_mov_b32_e32 v105, v64
	v_mov_b32_e32 v106, v64
	v_mov_b32_e32 v107, v64
	v_mov_b32_e32 v108, v64
	v_mov_b32_e32 v109, v64
	v_mov_b32_e32 v110, v64
	v_mov_b32_e32 v111, v64
	v_mov_b32_e32 v112, v64
	v_mov_b32_e32 v113, v64
	v_mov_b32_e32 v114, v64
	v_mov_b32_e32 v115, v64
	v_mov_b32_e32 v116, v64
	v_mov_b32_e32 v117, v64
	v_mov_b32_e32 v118, v64
	v_mov_b32_e32 v119, v64
	v_mov_b32_e32 v120, v64
	v_mov_b32_e32 v121, v64
	v_mov_b32_e32 v122, v64
	v_mov_b32_e32 v123, v64
	v_mov_b32_e32 v124, v64
	v_mov_b32_e32 v125, v64
	v_mov_b32_e32 v126, v64
	v_mov_b32_e32 v127, v64
	v_mov_b32_e32 v9, v132
	v_mov_b32_e32 v10, v133
	s_branch .LBB0_1599

	.amdhsa_kernel _Z4mega6Params
		.amdhsa_group_segment_fixed_size 81920
		.amdhsa_private_segment_fixed_size 0
		.amdhsa_kernarg_size 488
		.amdhsa_user_sgpr_count 2
		.amdhsa_user_sgpr_dispatch_ptr 0
		.amdhsa_user_sgpr_queue_ptr 0
		.amdhsa_user_sgpr_kernarg_segment_ptr 1
		.amdhsa_user_sgpr_dispatch_id 0
		.amdhsa_user_sgpr_kernarg_preload_length 0
		.amdhsa_user_sgpr_kernarg_preload_offset 0
		.amdhsa_user_sgpr_private_segment_size 0
		.amdhsa_uses_dynamic_stack 0
		.amdhsa_enable_private_segment 0
		.amdhsa_system_sgpr_workgroup_id_x 1
		.amdhsa_system_sgpr_workgroup_id_y 0
		.amdhsa_system_sgpr_workgroup_id_z 0
		.amdhsa_system_sgpr_workgroup_info 0
		.amdhsa_system_vgpr_workitem_id 2
		.amdhsa_next_free_vgpr 238
		.amdhsa_next_free_sgpr 102
		.amdhsa_accum_offset 240
		.amdhsa_reserve_vcc 1
		.amdhsa_float_round_mode_32 0
		.amdhsa_float_round_mode_16_64 0
		.amdhsa_float_denorm_mode_32 3
		.amdhsa_float_denorm_mode_16_64 3
		.amdhsa_dx10_clamp 1
		.amdhsa_ieee_mode 1
		.amdhsa_fp16_overflow 0
		.amdhsa_tg_split 0
		.amdhsa_exception_fp_ieee_invalid_op 0
		.amdhsa_exception_fp_denorm_src 0
		.amdhsa_exception_fp_ieee_div_zero 0
		.amdhsa_exception_fp_ieee_overflow 0
		.amdhsa_exception_fp_ieee_underflow 0
		.amdhsa_exception_fp_ieee_inexact 0
		.amdhsa_exception_int_div_zero 0
	.end_amdhsa_kernel

amdhsa.kernels:
  - .agpr_count:     0
    .args:
      - .offset:         0
        .size:           232
        .value_kind:     by_value
      - .offset:         232
        .size:           4
        .value_kind:     hidden_block_count_x
      - .offset:         236
        .size:           4
        .value_kind:     hidden_block_count_y
      - .offset:         240
        .size:           4
        .value_kind:     hidden_block_count_z
      - .offset:         244
        .size:           2
        .value_kind:     hidden_group_size_x
      - .offset:         246
        .size:           2
        .value_kind:     hidden_group_size_y
      - .offset:         248
        .size:           2
        .value_kind:     hidden_group_size_z
      - .offset:         250
        .size:           2
        .value_kind:     hidden_remainder_x
      - .offset:         252
        .size:           2
        .value_kind:     hidden_remainder_y
      - .offset:         254
        .size:           2
        .value_kind:     hidden_remainder_z
      - .offset:         272
        .size:           8
        .value_kind:     hidden_global_offset_x
      - .offset:         280
        .size:           8
        .value_kind:     hidden_global_offset_y
      - .offset:         288
        .size:           8
        .value_kind:     hidden_global_offset_z
      - .offset:         296
        .size:           2
        .value_kind:     hidden_grid_dims
      - .offset:         320
        .size:           8
        .value_kind:     hidden_multigrid_sync_arg
    .group_segment_fixed_size: 81920
    .kernarg_segment_align: 8
    .kernarg_segment_size: 488
    .language:       OpenCL C
    .language_version:
      - 2
      - 0
    .max_flat_workgroup_size: 256
    .name:           _Z4mega6Params
    .private_segment_fixed_size: 0
    .sgpr_count:     108
    .sgpr_spill_count: 88
    .symbol:         _Z4mega6Params.kd
    .uniform_work_group_size: 1
    .uses_dynamic_stack: false
    .vgpr_count:     238
    .vgpr_spill_count: 0
    .wavefront_size: 64
